# GEMM K-loops: first iteration peeled with C=0 MFMAs, accumulator zero-init v_movs removed
# speedup vs baseline: 1.0746x; 1.0085x over previous
.LBB0_92:
	s_ashr_i32 s53, s52, 31
	s_lshl_b64 s[42:43], s[52:53], 19
	s_add_u32 s54, s10, s42
	s_addc_u32 s55, s11, s43
	s_and_b64 s[42:43], s[40:41], exec
	s_cselect_b32 s45, s55, s5
	s_cselect_b32 s53, s54, s4
	s_ashr_i32 s47, s46, 31
	s_lshl_b64 s[42:43], s[46:47], 19
	s_add_u32 s56, s0, s42
	s_addc_u32 s57, s1, s43
	s_and_b64 s[42:43], s[40:41], exec
	s_cselect_b32 s47, s57, s19
	s_cselect_b32 s64, s56, s18
	s_add_u32 s4, s4, 0x40080
	s_addc_u32 s5, s5, 0
	s_add_u32 s65, s18, 0x100
	s_addc_u32 s66, s19, 0
	s_mov_b32 s67, -2
	s_add_u32 s18, s4, 0xfffc0080
	s_addc_u32 s19, s5, -1
	s_add_i32 s68, 0, 0x10000
	s_cmp_eq_u32 s67, 12
	s_cselect_b32 s43, s45, s19
	s_cselect_b32 s42, s53, s18
	s_cselect_b32 s19, s47, s66
	s_cselect_b32 s18, s64, s65
	s_add_i32 s70, 0, 0x14000
	v_add_u32_e32 v96, s68, v233
	v_add_u32_e32 v160, s70, v233
	ds_read_b128 v[44:47], v96
	ds_read_b128 v[64:67], v96 offset:1024
	ds_read_b128 v[76:79], v96 offset:2048
	ds_read_b128 v[96:99], v96 offset:3072
	ds_read_b128 v[116:119], v160
	ds_read_b128 v[136:139], v160 offset:1024
	ds_read_b128 v[156:159], v160 offset:2048
	ds_read_b128 v[160:163], v160 offset:3072
	v_lshl_add_u64 v[238:239], s[4:5], 0, v[182:183]
	s_add_i32 m0, s15, 0xc000
	ds_read_b128 v[164:167], v235
	ds_read_b128 v[186:189], v235 offset:1024
	ds_read_b128 v[190:193], v235 offset:2048
	ds_read_b128 v[194:197], v235 offset:3072
	ds_read_b128 v[198:201], v235 offset:4096
	ds_read_b128 v[202:205], v235 offset:5120
	ds_read_b128 v[206:209], v235 offset:6144
	ds_read_b128 v[210:213], v235 offset:7168
	global_load_lds_dwordx4 v[238:239], off
	v_lshl_add_u64 v[238:239], s[4:5], 0, v[184:185]
	s_add_i32 m0, s15, 0xe000
	s_nop 0
	global_load_lds_dwordx4 v[238:239], off
	s_waitcnt vmcnt(8)
	s_waitcnt lgkmcnt(0)
	s_barrier
	s_setprio 1
	s_waitcnt lgkmcnt(0)
	v_mfma_f32_16x16x32_bf16 v[152:155], v[44:47], v[164:167], 0
	v_mfma_f32_16x16x32_bf16 v[148:151], v[76:79], v[164:167], 0
	v_mfma_f32_16x16x32_bf16 v[132:135], v[44:47], v[190:193], 0
	v_mfma_f32_16x16x32_bf16 v[128:131], v[76:79], v[190:193], 0
	v_mfma_f32_16x16x32_bf16 v[112:115], v[44:47], v[198:201], 0
	v_mfma_f32_16x16x32_bf16 v[108:111], v[76:79], v[198:201], 0
	v_mfma_f32_16x16x32_bf16 v[92:95], v[44:47], v[206:209], 0
	v_mfma_f32_16x16x32_bf16 v[88:91], v[76:79], v[206:209], 0
	v_mfma_f32_16x16x32_bf16 v[152:155], v[64:67], v[186:189], v[152:155]
	v_mfma_f32_16x16x32_bf16 v[148:151], v[96:99], v[186:189], v[148:151]
	v_mfma_f32_16x16x32_bf16 v[132:135], v[64:67], v[194:197], v[132:135]
	v_mfma_f32_16x16x32_bf16 v[128:131], v[96:99], v[194:197], v[128:131]
	v_mfma_f32_16x16x32_bf16 v[112:115], v[64:67], v[202:205], v[112:115]
	v_mfma_f32_16x16x32_bf16 v[108:111], v[96:99], v[202:205], v[108:111]
	v_mfma_f32_16x16x32_bf16 v[92:95], v[64:67], v[210:213], v[92:95]
	v_mfma_f32_16x16x32_bf16 v[88:91], v[96:99], v[210:213], v[88:91]
	s_setprio 0
	s_setprio 1
	v_mfma_f32_16x16x32_bf16 v[144:147], v[116:119], v[164:167], 0
	v_mfma_f32_16x16x32_bf16 v[140:143], v[156:159], v[164:167], 0
	v_mfma_f32_16x16x32_bf16 v[124:127], v[116:119], v[190:193], 0
	v_mfma_f32_16x16x32_bf16 v[120:123], v[156:159], v[190:193], 0
	v_mfma_f32_16x16x32_bf16 v[104:107], v[116:119], v[198:201], 0
	v_mfma_f32_16x16x32_bf16 v[100:103], v[156:159], v[198:201], 0
	v_mfma_f32_16x16x32_bf16 v[84:87], v[116:119], v[206:209], 0
	v_mfma_f32_16x16x32_bf16 v[80:83], v[156:159], v[206:209], 0
	v_mfma_f32_16x16x32_bf16 v[144:147], v[136:139], v[186:189], v[144:147]
	v_mfma_f32_16x16x32_bf16 v[140:143], v[160:163], v[186:189], v[140:143]
	v_mfma_f32_16x16x32_bf16 v[124:127], v[136:139], v[194:197], v[124:127]
	v_mfma_f32_16x16x32_bf16 v[120:123], v[160:163], v[194:197], v[120:123]
	v_mfma_f32_16x16x32_bf16 v[104:107], v[136:139], v[202:205], v[104:107]
	v_mfma_f32_16x16x32_bf16 v[100:103], v[160:163], v[202:205], v[100:103]
	v_mfma_f32_16x16x32_bf16 v[84:87], v[136:139], v[210:213], v[84:87]
	v_mfma_f32_16x16x32_bf16 v[80:83], v[160:163], v[210:213], v[80:83]
	s_setprio 0
	s_barrier
	s_add_i32 s68, s68, s14
	v_lshl_add_u64 v[238:239], s[18:19], 0, v[2:3]
	s_mov_b32 m0, s68
	ds_read_b128 v[164:167], v235 offset:16384
	ds_read_b128 v[186:189], v235 offset:17408
	ds_read_b128 v[190:193], v235 offset:18432
	ds_read_b128 v[194:197], v235 offset:19456
	ds_read_b128 v[198:201], v235 offset:20480
	ds_read_b128 v[202:205], v235 offset:21504
	ds_read_b128 v[206:209], v235 offset:22528
	ds_read_b128 v[210:213], v235 offset:23552
	global_load_lds_dwordx4 v[238:239], off
	s_add_i32 m0, s68, 0x2000
	s_add_u32 s68, s18, 0x40000
	v_lshl_add_u64 v[240:241], s[18:19], 0, v[176:177]
	s_addc_u32 s69, s19, 0
	s_add_i32 s70, s70, s14
	global_load_lds_dwordx4 v[240:241], off
	v_lshl_add_u64 v[242:243], s[68:69], 0, v[2:3]
	s_mov_b32 m0, s70
	v_lshl_add_u64 v[244:245], s[42:43], 0, v[178:179]
	global_load_lds_dwordx4 v[242:243], off
	v_lshl_add_u64 v[242:243], s[68:69], 0, v[176:177]
	s_add_i32 m0, s70, 0x2000
	s_nop 0
	global_load_lds_dwordx4 v[242:243], off
	v_lshl_add_u64 v[242:243], s[42:43], 0, v[180:181]
	s_mov_b32 m0, s15
	s_nop 0
	global_load_lds_dwordx4 v[242:243], off
	s_mov_b32 m0, s58
	s_nop 0
	global_load_lds_dwordx4 v[244:245], off
	s_waitcnt vmcnt(8)
	s_waitcnt lgkmcnt(0)
	s_barrier
	s_setprio 1
	s_waitcnt lgkmcnt(0)
	v_mfma_f32_16x16x32_bf16 v[72:75], v[44:47], v[164:167], 0
	v_mfma_f32_16x16x32_bf16 v[68:71], v[76:79], v[164:167], 0
	v_mfma_f32_16x16x32_bf16 v[52:55], v[44:47], v[190:193], 0
	v_mfma_f32_16x16x32_bf16 v[48:51], v[76:79], v[190:193], 0
	v_mfma_f32_16x16x32_bf16 v[32:35], v[44:47], v[198:201], 0
	v_mfma_f32_16x16x32_bf16 v[28:31], v[76:79], v[198:201], 0
	v_mfma_f32_16x16x32_bf16 v[16:19], v[44:47], v[206:209], 0
	v_mfma_f32_16x16x32_bf16 v[12:15], v[76:79], v[206:209], 0
	v_mfma_f32_16x16x32_bf16 v[72:75], v[64:67], v[186:189], v[72:75]
	v_mfma_f32_16x16x32_bf16 v[68:71], v[96:99], v[186:189], v[68:71]
	v_mfma_f32_16x16x32_bf16 v[52:55], v[64:67], v[194:197], v[52:55]
	v_mfma_f32_16x16x32_bf16 v[48:51], v[96:99], v[194:197], v[48:51]
	v_mfma_f32_16x16x32_bf16 v[32:35], v[64:67], v[202:205], v[32:35]
	v_mfma_f32_16x16x32_bf16 v[28:31], v[96:99], v[202:205], v[28:31]
	v_mfma_f32_16x16x32_bf16 v[16:19], v[64:67], v[210:213], v[16:19]
	v_mfma_f32_16x16x32_bf16 v[12:15], v[96:99], v[210:213], v[12:15]
	s_setprio 0
	s_setprio 1
	v_mfma_f32_16x16x32_bf16 v[56:59], v[156:159], v[164:167], 0
	v_mfma_f32_16x16x32_bf16 v[40:43], v[116:119], v[190:193], 0
	v_mfma_f32_16x16x32_bf16 v[36:39], v[156:159], v[190:193], 0
	v_mfma_f32_16x16x32_bf16 v[24:27], v[116:119], v[198:201], 0
	v_mfma_f32_16x16x32_bf16 v[20:23], v[156:159], v[198:201], 0
	v_mfma_f32_16x16x32_bf16 v[8:11], v[116:119], v[206:209], 0
	v_mfma_f32_16x16x32_bf16 v[4:7], v[156:159], v[206:209], 0
	v_mfma_f32_16x16x32_bf16 v[44:47], v[116:119], v[164:167], 0
	v_mfma_f32_16x16x32_bf16 v[56:59], v[160:163], v[186:189], v[56:59]
	v_mfma_f32_16x16x32_bf16 v[40:43], v[136:139], v[194:197], v[40:43]
	v_mfma_f32_16x16x32_bf16 v[36:39], v[160:163], v[194:197], v[36:39]
	v_mfma_f32_16x16x32_bf16 v[24:27], v[136:139], v[202:205], v[24:27]
	v_mfma_f32_16x16x32_bf16 v[20:23], v[160:163], v[202:205], v[20:23]
	v_mfma_f32_16x16x32_bf16 v[8:11], v[136:139], v[210:213], v[8:11]
	v_mfma_f32_16x16x32_bf16 v[4:7], v[160:163], v[210:213], v[4:7]
	v_mfma_f32_16x16x32_bf16 v[44:47], v[136:139], v[186:189], v[44:47]
	s_setprio 0
	s_barrier
	s_add_i32 s68, 0, 0x18000
	s_add_i32 s69, 0, 0x1c000
	v_add_u32_e32 v96, s68, v233
	v_add_u32_e32 v160, s69, v233
	ds_read_b128 v[60:63], v96
	ds_read_b128 v[64:67], v96 offset:1024
	ds_read_b128 v[76:79], v96 offset:2048
	ds_read_b128 v[96:99], v96 offset:3072
	ds_read_b128 v[116:119], v160
	ds_read_b128 v[136:139], v160 offset:1024
	ds_read_b128 v[156:159], v160 offset:2048
	ds_read_b128 v[160:163], v160 offset:3072
	s_add_u32 s42, s42, 0x40000
	s_addc_u32 s43, s43, 0
	s_mov_b32 m0, s59
	v_lshl_add_u64 v[246:247], s[42:43], 0, v[180:181]
	ds_read_b128 v[164:167], v235 offset:32768
	ds_read_b128 v[186:189], v235 offset:33792
	ds_read_b128 v[190:193], v235 offset:34816
	ds_read_b128 v[194:197], v235 offset:35840
	ds_read_b128 v[198:201], v235 offset:36864
	ds_read_b128 v[202:205], v235 offset:37888
	ds_read_b128 v[206:209], v235 offset:38912
	ds_read_b128 v[210:213], v235 offset:39936
	global_load_lds_dwordx4 v[246:247], off
	v_lshl_add_u64 v[246:247], s[42:43], 0, v[178:179]
	s_mov_b32 m0, s60
	s_nop 0
	global_load_lds_dwordx4 v[246:247], off
	s_waitcnt vmcnt(8)
	s_waitcnt lgkmcnt(0)
	s_barrier
	s_setprio 1
	s_waitcnt lgkmcnt(0)
	v_mfma_f32_16x16x32_bf16 v[152:155], v[60:63], v[164:167], v[152:155]
	v_mfma_f32_16x16x32_bf16 v[148:151], v[76:79], v[164:167], v[148:151]
	v_mfma_f32_16x16x32_bf16 v[132:135], v[60:63], v[190:193], v[132:135]
	v_mfma_f32_16x16x32_bf16 v[128:131], v[76:79], v[190:193], v[128:131]
	v_mfma_f32_16x16x32_bf16 v[112:115], v[60:63], v[198:201], v[112:115]
	v_mfma_f32_16x16x32_bf16 v[108:111], v[76:79], v[198:201], v[108:111]
	v_mfma_f32_16x16x32_bf16 v[92:95], v[60:63], v[206:209], v[92:95]
	v_mfma_f32_16x16x32_bf16 v[88:91], v[76:79], v[206:209], v[88:91]
	v_mfma_f32_16x16x32_bf16 v[152:155], v[64:67], v[186:189], v[152:155]
	v_mfma_f32_16x16x32_bf16 v[148:151], v[96:99], v[186:189], v[148:151]
	v_mfma_f32_16x16x32_bf16 v[132:135], v[64:67], v[194:197], v[132:135]
	v_mfma_f32_16x16x32_bf16 v[128:131], v[96:99], v[194:197], v[128:131]
	v_mfma_f32_16x16x32_bf16 v[112:115], v[64:67], v[202:205], v[112:115]
	v_mfma_f32_16x16x32_bf16 v[108:111], v[96:99], v[202:205], v[108:111]
	v_mfma_f32_16x16x32_bf16 v[92:95], v[64:67], v[210:213], v[92:95]
	v_mfma_f32_16x16x32_bf16 v[88:91], v[96:99], v[210:213], v[88:91]
	s_setprio 0
	s_setprio 1
	v_mfma_f32_16x16x32_bf16 v[144:147], v[116:119], v[164:167], v[144:147]
	v_mfma_f32_16x16x32_bf16 v[140:143], v[156:159], v[164:167], v[140:143]
	v_mfma_f32_16x16x32_bf16 v[124:127], v[116:119], v[190:193], v[124:127]
	v_mfma_f32_16x16x32_bf16 v[120:123], v[156:159], v[190:193], v[120:123]
	v_mfma_f32_16x16x32_bf16 v[104:107], v[116:119], v[198:201], v[104:107]
	v_mfma_f32_16x16x32_bf16 v[100:103], v[156:159], v[198:201], v[100:103]
	v_mfma_f32_16x16x32_bf16 v[84:87], v[116:119], v[206:209], v[84:87]
	v_mfma_f32_16x16x32_bf16 v[80:83], v[156:159], v[206:209], v[80:83]
	v_mfma_f32_16x16x32_bf16 v[144:147], v[136:139], v[186:189], v[144:147]
	v_mfma_f32_16x16x32_bf16 v[140:143], v[160:163], v[186:189], v[140:143]
	v_mfma_f32_16x16x32_bf16 v[124:127], v[136:139], v[194:197], v[124:127]
	v_mfma_f32_16x16x32_bf16 v[120:123], v[160:163], v[194:197], v[120:123]
	v_mfma_f32_16x16x32_bf16 v[104:107], v[136:139], v[202:205], v[104:107]
	v_mfma_f32_16x16x32_bf16 v[100:103], v[160:163], v[202:205], v[100:103]
	v_mfma_f32_16x16x32_bf16 v[84:87], v[136:139], v[210:213], v[84:87]
	v_mfma_f32_16x16x32_bf16 v[80:83], v[160:163], v[210:213], v[80:83]
	s_setprio 0
	s_barrier
	s_add_i32 s42, s68, s14
	v_lshl_add_u64 v[238:239], v[238:239], 0, s[16:17]
	s_mov_b32 m0, s42
	ds_read_b128 v[164:167], v235 offset:49152
	ds_read_b128 v[186:189], v235 offset:50176
	ds_read_b128 v[190:193], v235 offset:51200
	ds_read_b128 v[194:197], v235 offset:52224
	ds_read_b128 v[198:201], v235 offset:53248
	ds_read_b128 v[202:205], v235 offset:54272
	ds_read_b128 v[206:209], v235 offset:55296
	ds_read_b128 v[210:213], v235 offset:56320
	global_load_lds_dwordx4 v[238:239], off
	s_add_i32 m0, s42, 0x2000
	s_add_u32 s18, s18, 0x40080
	v_lshl_add_u64 v[238:239], v[240:241], 0, s[16:17]
	s_addc_u32 s19, s19, 0
	s_add_i32 s42, s69, s14
	global_load_lds_dwordx4 v[238:239], off
	v_lshl_add_u64 v[238:239], s[18:19], 0, v[2:3]
	s_mov_b32 m0, s42
	s_nop 0
	global_load_lds_dwordx4 v[238:239], off
	v_lshl_add_u64 v[238:239], s[18:19], 0, v[176:177]
	s_add_i32 m0, s42, 0x2000
	s_nop 0
	global_load_lds_dwordx4 v[238:239], off
	v_lshl_add_u64 v[238:239], v[242:243], 0, s[16:17]
	s_mov_b32 m0, s61
	s_nop 0
	global_load_lds_dwordx4 v[238:239], off
	v_lshl_add_u64 v[238:239], v[244:245], 0, s[16:17]
	s_mov_b32 m0, s62
	s_nop 0
	global_load_lds_dwordx4 v[238:239], off
	s_waitcnt vmcnt(8)
	s_waitcnt lgkmcnt(0)
	s_barrier
	s_setprio 1
	s_waitcnt lgkmcnt(0)
	v_mfma_f32_16x16x32_bf16 v[72:75], v[60:63], v[164:167], v[72:75]
	v_mfma_f32_16x16x32_bf16 v[68:71], v[76:79], v[164:167], v[68:71]
	v_mfma_f32_16x16x32_bf16 v[52:55], v[60:63], v[190:193], v[52:55]
	v_mfma_f32_16x16x32_bf16 v[48:51], v[76:79], v[190:193], v[48:51]
	v_mfma_f32_16x16x32_bf16 v[32:35], v[60:63], v[198:201], v[32:35]
	v_mfma_f32_16x16x32_bf16 v[28:31], v[76:79], v[198:201], v[28:31]
	v_mfma_f32_16x16x32_bf16 v[16:19], v[60:63], v[206:209], v[16:19]
	v_mfma_f32_16x16x32_bf16 v[12:15], v[76:79], v[206:209], v[12:15]
	v_mfma_f32_16x16x32_bf16 v[72:75], v[64:67], v[186:189], v[72:75]
	v_mfma_f32_16x16x32_bf16 v[68:71], v[96:99], v[186:189], v[68:71]
	v_mfma_f32_16x16x32_bf16 v[52:55], v[64:67], v[194:197], v[52:55]
	v_mfma_f32_16x16x32_bf16 v[48:51], v[96:99], v[194:197], v[48:51]
	v_mfma_f32_16x16x32_bf16 v[32:35], v[64:67], v[202:205], v[32:35]
	v_mfma_f32_16x16x32_bf16 v[28:31], v[96:99], v[202:205], v[28:31]
	v_mfma_f32_16x16x32_bf16 v[16:19], v[64:67], v[210:213], v[16:19]
	v_mfma_f32_16x16x32_bf16 v[12:15], v[96:99], v[210:213], v[12:15]
	s_setprio 0
	s_setprio 1
	v_mfma_f32_16x16x32_bf16 v[44:47], v[116:119], v[164:167], v[44:47]
	v_mfma_f32_16x16x32_bf16 v[60:63], v[136:139], v[186:189], v[44:47]
	v_mfma_f32_16x16x32_bf16 v[44:47], v[156:159], v[164:167], v[56:59]
	v_mfma_f32_16x16x32_bf16 v[40:43], v[116:119], v[190:193], v[40:43]
	v_mfma_f32_16x16x32_bf16 v[36:39], v[156:159], v[190:193], v[36:39]
	v_mfma_f32_16x16x32_bf16 v[24:27], v[116:119], v[198:201], v[24:27]
	v_mfma_f32_16x16x32_bf16 v[20:23], v[156:159], v[198:201], v[20:23]
	v_mfma_f32_16x16x32_bf16 v[8:11], v[116:119], v[206:209], v[8:11]
	v_mfma_f32_16x16x32_bf16 v[4:7], v[156:159], v[206:209], v[4:7]
	v_mfma_f32_16x16x32_bf16 v[56:59], v[160:163], v[186:189], v[44:47]
	v_mfma_f32_16x16x32_bf16 v[40:43], v[136:139], v[194:197], v[40:43]
	v_mfma_f32_16x16x32_bf16 v[36:39], v[160:163], v[194:197], v[36:39]
	v_mfma_f32_16x16x32_bf16 v[24:27], v[136:139], v[202:205], v[24:27]
	v_mfma_f32_16x16x32_bf16 v[20:23], v[160:163], v[202:205], v[20:23]
	v_mfma_f32_16x16x32_bf16 v[8:11], v[136:139], v[210:213], v[8:11]
	v_mfma_f32_16x16x32_bf16 v[4:7], v[160:163], v[210:213], v[4:7]
	s_setprio 0
	s_barrier
	s_add_i32 s67, s67, 2
	s_add_u32 s4, s4, 0x100
	s_addc_u32 s5, s5, 0
	s_add_u32 s65, s65, 0x100
	s_addc_u32 s66, s66, 0
	s_cmp_gt_u32 s67, 13

.LBB0_212:
	s_ashr_i32 s41, s40, 31
	s_lshl_b64 s[14:15], s[40:41], 19
	s_add_u32 s42, s50, s14
	s_addc_u32 s43, s51, s15
	s_and_b64 s[14:15], s[28:29], exec
	s_cselect_b32 s14, s43, s5
	s_cselect_b32 s15, s42, s4
	s_ashr_i32 s31, s30, 31
	s_lshl_b64 s[44:45], s[30:31], 19
	s_add_u32 s44, s10, s44
	s_addc_u32 s45, s11, s45
	s_and_b64 s[48:49], s[28:29], exec
	s_cselect_b32 s31, s45, s19
	s_cselect_b32 s41, s44, s18
	s_add_u32 s4, s4, 0x40080
	s_addc_u32 s5, s5, 0
	s_add_u32 s59, s18, 0x100
	s_addc_u32 s60, s19, 0
	s_mov_b32 s61, -2
	s_add_u32 s18, s4, 0xfffc0080
	s_addc_u32 s19, s5, -1
	s_add_i32 s62, 0, 0x10000
	s_cmp_eq_u32 s61, 12
	s_cselect_b32 s49, s14, s19
	s_cselect_b32 s48, s15, s18
	s_cselect_b32 s19, s31, s60
	s_cselect_b32 s18, s41, s59
	s_add_i32 s64, 0, 0x14000
	v_add_u32_e32 v144, s62, v180
	v_add_u32_e32 v166, s64, v180
	ds_read_b128 v[132:135], v144
	ds_read_b128 v[136:139], v144 offset:1024
	ds_read_b128 v[140:143], v144 offset:2048
	ds_read_b128 v[144:147], v144 offset:3072
	ds_read_b128 v[158:161], v166
	ds_read_b128 v[162:165], v166 offset:1024
	ds_read_b128 v[176:179], v166 offset:2048
	ds_read_b128 v[184:187], v166 offset:3072
	v_lshl_add_u64 v[166:167], s[4:5], 0, v[154:155]
	s_add_i32 m0, s47, 0xc000
	ds_read_b128 v[188:191], v182
	ds_read_b128 v[192:195], v182 offset:1024
	ds_read_b128 v[196:199], v182 offset:2048
	ds_read_b128 v[200:203], v182 offset:3072
	ds_read_b128 v[204:207], v182 offset:4096
	ds_read_b128 v[208:211], v182 offset:5120
	ds_read_b128 v[234:237], v182 offset:6144
	ds_read_b128 v[238:241], v182 offset:7168
	global_load_lds_dwordx4 v[166:167], off
	v_lshl_add_u64 v[166:167], s[4:5], 0, v[156:157]
	s_add_i32 m0, s47, 0xe000
	s_nop 0
	global_load_lds_dwordx4 v[166:167], off
	s_waitcnt vmcnt(8)
	s_waitcnt lgkmcnt(0)
	s_barrier
	s_setprio 1
	s_waitcnt lgkmcnt(0)
	v_mfma_f32_16x16x32_bf16 v[128:131], v[132:135], v[188:191], 0
	v_mfma_f32_16x16x32_bf16 v[124:127], v[140:143], v[188:191], 0
	v_mfma_f32_16x16x32_bf16 v[116:119], v[132:135], v[196:199], 0
	v_mfma_f32_16x16x32_bf16 v[108:111], v[140:143], v[196:199], 0
	v_mfma_f32_16x16x32_bf16 v[100:103], v[132:135], v[204:207], 0
	v_mfma_f32_16x16x32_bf16 v[92:95], v[140:143], v[204:207], 0
	v_mfma_f32_16x16x32_bf16 v[84:87], v[132:135], v[234:237], 0
	v_mfma_f32_16x16x32_bf16 v[76:79], v[140:143], v[234:237], 0
	v_mfma_f32_16x16x32_bf16 v[128:131], v[136:139], v[192:195], v[128:131]
	v_mfma_f32_16x16x32_bf16 v[124:127], v[144:147], v[192:195], v[124:127]
	v_mfma_f32_16x16x32_bf16 v[116:119], v[136:139], v[200:203], v[116:119]
	v_mfma_f32_16x16x32_bf16 v[108:111], v[144:147], v[200:203], v[108:111]
	v_mfma_f32_16x16x32_bf16 v[100:103], v[136:139], v[208:211], v[100:103]
	v_mfma_f32_16x16x32_bf16 v[92:95], v[144:147], v[208:211], v[92:95]
	v_mfma_f32_16x16x32_bf16 v[84:87], v[136:139], v[238:241], v[84:87]
	v_mfma_f32_16x16x32_bf16 v[76:79], v[144:147], v[238:241], v[76:79]
	s_setprio 0
	s_setprio 1
	v_mfma_f32_16x16x32_bf16 v[120:123], v[158:161], v[188:191], 0
	v_mfma_f32_16x16x32_bf16 v[112:115], v[176:179], v[188:191], 0
	v_mfma_f32_16x16x32_bf16 v[104:107], v[158:161], v[196:199], 0
	v_mfma_f32_16x16x32_bf16 v[96:99], v[176:179], v[196:199], 0
	v_mfma_f32_16x16x32_bf16 v[88:91], v[158:161], v[204:207], 0
	v_mfma_f32_16x16x32_bf16 v[80:83], v[176:179], v[204:207], 0
	v_mfma_f32_16x16x32_bf16 v[72:75], v[158:161], v[234:237], 0
	v_mfma_f32_16x16x32_bf16 v[68:71], v[176:179], v[234:237], 0
	v_mfma_f32_16x16x32_bf16 v[120:123], v[162:165], v[192:195], v[120:123]
	v_mfma_f32_16x16x32_bf16 v[112:115], v[184:187], v[192:195], v[112:115]
	v_mfma_f32_16x16x32_bf16 v[104:107], v[162:165], v[200:203], v[104:107]
	v_mfma_f32_16x16x32_bf16 v[96:99], v[184:187], v[200:203], v[96:99]
	v_mfma_f32_16x16x32_bf16 v[88:91], v[162:165], v[208:211], v[88:91]
	v_mfma_f32_16x16x32_bf16 v[80:83], v[184:187], v[208:211], v[80:83]
	v_mfma_f32_16x16x32_bf16 v[72:75], v[162:165], v[238:241], v[72:75]
	v_mfma_f32_16x16x32_bf16 v[68:71], v[184:187], v[238:241], v[68:71]
	s_setprio 0
	s_barrier
	s_add_i32 s62, s62, s34
	v_lshl_add_u64 v[166:167], s[18:19], 0, v[2:3]
	s_mov_b32 m0, s62
	ds_read_b128 v[188:191], v182 offset:16384
	ds_read_b128 v[192:195], v182 offset:17408
	ds_read_b128 v[196:199], v182 offset:18432
	ds_read_b128 v[200:203], v182 offset:19456
	ds_read_b128 v[204:207], v182 offset:20480
	ds_read_b128 v[208:211], v182 offset:21504
	ds_read_b128 v[234:237], v182 offset:22528
	ds_read_b128 v[238:241], v182 offset:23552
	global_load_lds_dwordx4 v[166:167], off
	s_add_i32 m0, s62, 0x2000
	s_add_u32 s62, s18, 0x40000
	v_lshl_add_u64 v[212:213], s[18:19], 0, v[152:153]
	s_addc_u32 s63, s19, 0
	s_add_i32 s64, s64, s34
	global_load_lds_dwordx4 v[212:213], off
	v_lshl_add_u64 v[242:243], s[62:63], 0, v[2:3]
	s_mov_b32 m0, s64
	v_lshl_add_u64 v[244:245], s[48:49], 0, v[150:151]
	global_load_lds_dwordx4 v[242:243], off
	v_lshl_add_u64 v[242:243], s[62:63], 0, v[152:153]
	s_add_i32 m0, s64, 0x2000
	s_nop 0
	global_load_lds_dwordx4 v[242:243], off
	v_lshl_add_u64 v[242:243], s[48:49], 0, v[148:149]
	s_mov_b32 m0, s47
	s_nop 0
	global_load_lds_dwordx4 v[242:243], off
	s_mov_b32 m0, s52
	s_nop 0
	global_load_lds_dwordx4 v[244:245], off
	s_waitcnt vmcnt(8)
	s_waitcnt lgkmcnt(0)
	s_barrier
	s_setprio 1
	s_waitcnt lgkmcnt(0)
	v_mfma_f32_16x16x32_bf16 v[64:67], v[132:135], v[188:191], 0
	v_mfma_f32_16x16x32_bf16 v[60:63], v[140:143], v[188:191], 0
	v_mfma_f32_16x16x32_bf16 v[52:55], v[132:135], v[196:199], 0
	v_mfma_f32_16x16x32_bf16 v[44:47], v[140:143], v[196:199], 0
	v_mfma_f32_16x16x32_bf16 v[36:39], v[132:135], v[204:207], 0
	v_mfma_f32_16x16x32_bf16 v[28:31], v[140:143], v[204:207], 0
	v_mfma_f32_16x16x32_bf16 v[20:23], v[132:135], v[234:237], 0
	v_mfma_f32_16x16x32_bf16 v[12:15], v[140:143], v[234:237], 0
	v_mfma_f32_16x16x32_bf16 v[64:67], v[136:139], v[192:195], v[64:67]
	v_mfma_f32_16x16x32_bf16 v[60:63], v[144:147], v[192:195], v[60:63]
	v_mfma_f32_16x16x32_bf16 v[52:55], v[136:139], v[200:203], v[52:55]
	v_mfma_f32_16x16x32_bf16 v[44:47], v[144:147], v[200:203], v[44:47]
	v_mfma_f32_16x16x32_bf16 v[36:39], v[136:139], v[208:211], v[36:39]
	v_mfma_f32_16x16x32_bf16 v[28:31], v[144:147], v[208:211], v[28:31]
	v_mfma_f32_16x16x32_bf16 v[20:23], v[136:139], v[238:241], v[20:23]
	v_mfma_f32_16x16x32_bf16 v[12:15], v[144:147], v[238:241], v[12:15]
	s_setprio 0
	s_setprio 1
	v_mfma_f32_16x16x32_bf16 v[56:59], v[158:161], v[188:191], 0
	v_mfma_f32_16x16x32_bf16 v[48:51], v[176:179], v[188:191], 0
	v_mfma_f32_16x16x32_bf16 v[40:43], v[158:161], v[196:199], 0
	v_mfma_f32_16x16x32_bf16 v[32:35], v[176:179], v[196:199], 0
	v_mfma_f32_16x16x32_bf16 v[24:27], v[158:161], v[204:207], 0
	v_mfma_f32_16x16x32_bf16 v[16:19], v[176:179], v[204:207], 0
	v_mfma_f32_16x16x32_bf16 v[8:11], v[158:161], v[234:237], 0
	v_mfma_f32_16x16x32_bf16 v[4:7], v[176:179], v[234:237], 0
	v_mfma_f32_16x16x32_bf16 v[56:59], v[162:165], v[192:195], v[56:59]
	v_mfma_f32_16x16x32_bf16 v[48:51], v[184:187], v[192:195], v[48:51]
	v_mfma_f32_16x16x32_bf16 v[40:43], v[162:165], v[200:203], v[40:43]
	v_mfma_f32_16x16x32_bf16 v[32:35], v[184:187], v[200:203], v[32:35]
	v_mfma_f32_16x16x32_bf16 v[24:27], v[162:165], v[208:211], v[24:27]
	v_mfma_f32_16x16x32_bf16 v[16:19], v[184:187], v[208:211], v[16:19]
	v_mfma_f32_16x16x32_bf16 v[8:11], v[162:165], v[238:241], v[8:11]
	v_mfma_f32_16x16x32_bf16 v[4:7], v[184:187], v[238:241], v[4:7]
	s_setprio 0
	s_barrier
	s_add_i32 s62, 0, 0x18000
	s_add_i32 s63, 0, 0x1c000
	v_add_u32_e32 v144, s62, v180
	v_add_u32_e32 v183, s63, v180
	ds_read_b128 v[132:135], v144
	ds_read_b128 v[136:139], v144 offset:1024
	ds_read_b128 v[140:143], v144 offset:2048
	ds_read_b128 v[144:147], v144 offset:3072
	ds_read_b128 v[158:161], v183
	ds_read_b128 v[162:165], v183 offset:1024
	ds_read_b128 v[176:179], v183 offset:2048
	ds_read_b128 v[184:187], v183 offset:3072
	s_add_u32 s48, s48, 0x40000
	s_addc_u32 s49, s49, 0
	s_mov_b32 m0, s53
	v_lshl_add_u64 v[246:247], s[48:49], 0, v[148:149]
	ds_read_b128 v[188:191], v182 offset:32768
	ds_read_b128 v[192:195], v182 offset:33792
	ds_read_b128 v[196:199], v182 offset:34816
	ds_read_b128 v[200:203], v182 offset:35840
	ds_read_b128 v[204:207], v182 offset:36864
	ds_read_b128 v[208:211], v182 offset:37888
	ds_read_b128 v[234:237], v182 offset:38912
	ds_read_b128 v[238:241], v182 offset:39936
	global_load_lds_dwordx4 v[246:247], off
	v_lshl_add_u64 v[246:247], s[48:49], 0, v[150:151]
	s_mov_b32 m0, s54
	s_nop 0
	global_load_lds_dwordx4 v[246:247], off
	s_waitcnt vmcnt(8)
	s_waitcnt lgkmcnt(0)
	s_barrier
	s_setprio 1
	s_waitcnt lgkmcnt(0)
	v_mfma_f32_16x16x32_bf16 v[128:131], v[132:135], v[188:191], v[128:131]
	v_mfma_f32_16x16x32_bf16 v[124:127], v[140:143], v[188:191], v[124:127]
	v_mfma_f32_16x16x32_bf16 v[116:119], v[132:135], v[196:199], v[116:119]
	v_mfma_f32_16x16x32_bf16 v[108:111], v[140:143], v[196:199], v[108:111]
	v_mfma_f32_16x16x32_bf16 v[100:103], v[132:135], v[204:207], v[100:103]
	v_mfma_f32_16x16x32_bf16 v[92:95], v[140:143], v[204:207], v[92:95]
	v_mfma_f32_16x16x32_bf16 v[84:87], v[132:135], v[234:237], v[84:87]
	v_mfma_f32_16x16x32_bf16 v[76:79], v[140:143], v[234:237], v[76:79]
	v_mfma_f32_16x16x32_bf16 v[128:131], v[136:139], v[192:195], v[128:131]
	v_mfma_f32_16x16x32_bf16 v[124:127], v[144:147], v[192:195], v[124:127]
	v_mfma_f32_16x16x32_bf16 v[116:119], v[136:139], v[200:203], v[116:119]
	v_mfma_f32_16x16x32_bf16 v[108:111], v[144:147], v[200:203], v[108:111]
	v_mfma_f32_16x16x32_bf16 v[100:103], v[136:139], v[208:211], v[100:103]
	v_mfma_f32_16x16x32_bf16 v[92:95], v[144:147], v[208:211], v[92:95]
	v_mfma_f32_16x16x32_bf16 v[84:87], v[136:139], v[238:241], v[84:87]
	v_mfma_f32_16x16x32_bf16 v[76:79], v[144:147], v[238:241], v[76:79]
	s_setprio 0
	s_setprio 1
	v_mfma_f32_16x16x32_bf16 v[120:123], v[158:161], v[188:191], v[120:123]
	v_mfma_f32_16x16x32_bf16 v[112:115], v[176:179], v[188:191], v[112:115]
	v_mfma_f32_16x16x32_bf16 v[104:107], v[158:161], v[196:199], v[104:107]
	v_mfma_f32_16x16x32_bf16 v[96:99], v[176:179], v[196:199], v[96:99]
	v_mfma_f32_16x16x32_bf16 v[88:91], v[158:161], v[204:207], v[88:91]
	v_mfma_f32_16x16x32_bf16 v[80:83], v[176:179], v[204:207], v[80:83]
	v_mfma_f32_16x16x32_bf16 v[72:75], v[158:161], v[234:237], v[72:75]
	v_mfma_f32_16x16x32_bf16 v[68:71], v[176:179], v[234:237], v[68:71]
	v_mfma_f32_16x16x32_bf16 v[120:123], v[162:165], v[192:195], v[120:123]
	v_mfma_f32_16x16x32_bf16 v[112:115], v[184:187], v[192:195], v[112:115]
	v_mfma_f32_16x16x32_bf16 v[104:107], v[162:165], v[200:203], v[104:107]
	v_mfma_f32_16x16x32_bf16 v[96:99], v[184:187], v[200:203], v[96:99]
	v_mfma_f32_16x16x32_bf16 v[88:91], v[162:165], v[208:211], v[88:91]
	v_mfma_f32_16x16x32_bf16 v[80:83], v[184:187], v[208:211], v[80:83]
	v_mfma_f32_16x16x32_bf16 v[72:75], v[162:165], v[238:241], v[72:75]
	v_mfma_f32_16x16x32_bf16 v[68:71], v[184:187], v[238:241], v[68:71]
	s_setprio 0
	s_barrier
	s_add_i32 s48, s62, s34
	v_lshl_add_u64 v[166:167], v[166:167], 0, s[16:17]
	s_mov_b32 m0, s48
	ds_read_b128 v[188:191], v182 offset:49152
	ds_read_b128 v[192:195], v182 offset:50176
	ds_read_b128 v[196:199], v182 offset:51200
	ds_read_b128 v[200:203], v182 offset:52224
	ds_read_b128 v[204:207], v182 offset:53248
	ds_read_b128 v[208:211], v182 offset:54272
	ds_read_b128 v[234:237], v182 offset:55296
	ds_read_b128 v[238:241], v182 offset:56320
	global_load_lds_dwordx4 v[166:167], off
	s_add_i32 m0, s48, 0x2000
	s_add_u32 s18, s18, 0x40080
	v_lshl_add_u64 v[166:167], v[212:213], 0, s[16:17]
	s_addc_u32 s19, s19, 0
	s_add_i32 s48, s63, s34
	global_load_lds_dwordx4 v[166:167], off
	v_lshl_add_u64 v[166:167], s[18:19], 0, v[2:3]
	s_mov_b32 m0, s48
	s_nop 0
	global_load_lds_dwordx4 v[166:167], off
	v_lshl_add_u64 v[166:167], s[18:19], 0, v[152:153]
	s_add_i32 m0, s48, 0x2000
	s_nop 0
	global_load_lds_dwordx4 v[166:167], off
	v_lshl_add_u64 v[166:167], v[242:243], 0, s[16:17]
	s_mov_b32 m0, s55
	s_nop 0
	global_load_lds_dwordx4 v[166:167], off
	v_lshl_add_u64 v[166:167], v[244:245], 0, s[16:17]
	s_mov_b32 m0, s56
	s_nop 0
	global_load_lds_dwordx4 v[166:167], off
	s_waitcnt vmcnt(8)
	s_waitcnt lgkmcnt(0)
	s_barrier
	s_setprio 1
	s_waitcnt lgkmcnt(0)
	v_mfma_f32_16x16x32_bf16 v[64:67], v[132:135], v[188:191], v[64:67]
	v_mfma_f32_16x16x32_bf16 v[60:63], v[140:143], v[188:191], v[60:63]
	v_mfma_f32_16x16x32_bf16 v[52:55], v[132:135], v[196:199], v[52:55]
	v_mfma_f32_16x16x32_bf16 v[44:47], v[140:143], v[196:199], v[44:47]
	v_mfma_f32_16x16x32_bf16 v[36:39], v[132:135], v[204:207], v[36:39]
	v_mfma_f32_16x16x32_bf16 v[28:31], v[140:143], v[204:207], v[28:31]
	v_mfma_f32_16x16x32_bf16 v[20:23], v[132:135], v[234:237], v[20:23]
	v_mfma_f32_16x16x32_bf16 v[12:15], v[140:143], v[234:237], v[12:15]
	v_mfma_f32_16x16x32_bf16 v[64:67], v[136:139], v[192:195], v[64:67]
	v_mfma_f32_16x16x32_bf16 v[60:63], v[144:147], v[192:195], v[60:63]
	v_mfma_f32_16x16x32_bf16 v[52:55], v[136:139], v[200:203], v[52:55]
	v_mfma_f32_16x16x32_bf16 v[44:47], v[144:147], v[200:203], v[44:47]
	v_mfma_f32_16x16x32_bf16 v[36:39], v[136:139], v[208:211], v[36:39]
	v_mfma_f32_16x16x32_bf16 v[28:31], v[144:147], v[208:211], v[28:31]
	v_mfma_f32_16x16x32_bf16 v[20:23], v[136:139], v[238:241], v[20:23]
	v_mfma_f32_16x16x32_bf16 v[12:15], v[144:147], v[238:241], v[12:15]
	s_setprio 0
	s_setprio 1
	v_mfma_f32_16x16x32_bf16 v[56:59], v[158:161], v[188:191], v[56:59]
	v_mfma_f32_16x16x32_bf16 v[48:51], v[176:179], v[188:191], v[48:51]
	v_mfma_f32_16x16x32_bf16 v[40:43], v[158:161], v[196:199], v[40:43]
	v_mfma_f32_16x16x32_bf16 v[32:35], v[176:179], v[196:199], v[32:35]
	v_mfma_f32_16x16x32_bf16 v[24:27], v[158:161], v[204:207], v[24:27]
	v_mfma_f32_16x16x32_bf16 v[16:19], v[176:179], v[204:207], v[16:19]
	v_mfma_f32_16x16x32_bf16 v[8:11], v[158:161], v[234:237], v[8:11]
	v_mfma_f32_16x16x32_bf16 v[4:7], v[176:179], v[234:237], v[4:7]
	v_mfma_f32_16x16x32_bf16 v[56:59], v[162:165], v[192:195], v[56:59]
	v_mfma_f32_16x16x32_bf16 v[48:51], v[184:187], v[192:195], v[48:51]
	v_mfma_f32_16x16x32_bf16 v[40:43], v[162:165], v[200:203], v[40:43]
	v_mfma_f32_16x16x32_bf16 v[32:35], v[184:187], v[200:203], v[32:35]
	v_mfma_f32_16x16x32_bf16 v[24:27], v[162:165], v[208:211], v[24:27]
	v_mfma_f32_16x16x32_bf16 v[16:19], v[184:187], v[208:211], v[16:19]
	v_mfma_f32_16x16x32_bf16 v[8:11], v[162:165], v[238:241], v[8:11]
	v_mfma_f32_16x16x32_bf16 v[4:7], v[184:187], v[238:241], v[4:7]
	s_setprio 0
	s_barrier
	s_add_i32 s61, s61, 2
	s_add_u32 s4, s4, 0x100
	s_addc_u32 s5, s5, 0
	s_add_u32 s59, s59, 0x100
	s_addc_u32 s60, s60, 0
	s_cmp_gt_u32 s61, 13

.LBB0_773:
	s_ashr_i32 s25, s24, 31
	s_lshl_b64 s[14:15], s[24:25], 19
	s_add_u32 s26, s10, s14
	s_addc_u32 s27, s11, s15
	s_and_b64 s[14:15], s[44:45], exec
	s_cselect_b32 s14, s27, s31
	s_cselect_b32 s15, s26, s30
	s_ashr_i32 s23, s22, 31
	s_lshl_b64 s[28:29], s[22:23], 19
	s_add_u32 s28, s50, s28
	s_addc_u32 s29, s51, s29
	s_and_b64 s[48:49], s[44:45], exec
	s_cselect_b32 s23, s29, s47
	s_cselect_b32 s25, s28, s46
	s_add_u32 s30, s30, 0x40080
	s_addc_u32 s31, s31, 0
	s_add_u32 s59, s46, 0x100
	s_addc_u32 s60, s47, 0
	s_mov_b32 s61, -2
	s_waitcnt lgkmcnt(0)
	s_add_u32 s46, s30, 0xfffc0080
	s_addc_u32 s47, s31, -1
	s_add_i32 s62, 0, 0x10000
	s_cmp_eq_u32 s61, 12
	s_cselect_b32 s49, s14, s47
	s_cselect_b32 s48, s15, s46
	s_cselect_b32 s47, s23, s60
	s_cselect_b32 s46, s25, s59
	s_add_i32 s64, 0, 0x14000
	v_add_u32_e32 v144, s62, v192
	v_add_u32_e32 v166, s64, v192
	ds_read_b128 v[132:135], v144
	ds_read_b128 v[136:139], v144 offset:1024
	ds_read_b128 v[140:143], v144 offset:2048
	ds_read_b128 v[144:147], v144 offset:3072
	ds_read_b128 v[148:151], v166
	ds_read_b128 v[152:155], v166 offset:1024
	ds_read_b128 v[176:179], v166 offset:2048
	ds_read_b128 v[180:183], v166 offset:3072
	v_lshl_add_u64 v[166:167], s[30:31], 0, v[162:163]
	s_add_i32 m0, s53, 0xc000
	ds_read_b128 v[184:187], v194
	ds_read_b128 v[188:191], v194 offset:1024
	ds_read_b128 v[196:199], v194 offset:2048
	ds_read_b128 v[200:203], v194 offset:3072
	ds_read_b128 v[204:207], v194 offset:4096
	ds_read_b128 v[208:211], v194 offset:5120
	ds_read_b128 v[234:237], v194 offset:6144
	ds_read_b128 v[238:241], v194 offset:7168
	global_load_lds_dwordx4 v[166:167], off
	v_lshl_add_u64 v[166:167], s[30:31], 0, v[164:165]
	s_add_i32 m0, s53, 0xe000
	s_nop 0
	global_load_lds_dwordx4 v[166:167], off
	s_waitcnt vmcnt(8)
	s_waitcnt lgkmcnt(0)
	s_barrier
	s_setprio 1
	s_waitcnt lgkmcnt(0)
	v_mfma_f32_16x16x32_bf16 v[128:131], v[132:135], v[184:187], 0
	v_mfma_f32_16x16x32_bf16 v[124:127], v[140:143], v[184:187], 0
	v_mfma_f32_16x16x32_bf16 v[112:115], v[132:135], v[196:199], 0
	v_mfma_f32_16x16x32_bf16 v[108:111], v[140:143], v[196:199], 0
	v_mfma_f32_16x16x32_bf16 v[96:99], v[132:135], v[204:207], 0
	v_mfma_f32_16x16x32_bf16 v[92:95], v[140:143], v[204:207], 0
	v_mfma_f32_16x16x32_bf16 v[80:83], v[132:135], v[234:237], 0
	v_mfma_f32_16x16x32_bf16 v[76:79], v[140:143], v[234:237], 0
	v_mfma_f32_16x16x32_bf16 v[128:131], v[136:139], v[188:191], v[128:131]
	v_mfma_f32_16x16x32_bf16 v[124:127], v[144:147], v[188:191], v[124:127]
	v_mfma_f32_16x16x32_bf16 v[112:115], v[136:139], v[200:203], v[112:115]
	v_mfma_f32_16x16x32_bf16 v[108:111], v[144:147], v[200:203], v[108:111]
	v_mfma_f32_16x16x32_bf16 v[96:99], v[136:139], v[208:211], v[96:99]
	v_mfma_f32_16x16x32_bf16 v[92:95], v[144:147], v[208:211], v[92:95]
	v_mfma_f32_16x16x32_bf16 v[80:83], v[136:139], v[238:241], v[80:83]
	v_mfma_f32_16x16x32_bf16 v[76:79], v[144:147], v[238:241], v[76:79]
	s_setprio 0
	s_setprio 1
	v_mfma_f32_16x16x32_bf16 v[120:123], v[148:151], v[184:187], 0
	v_mfma_f32_16x16x32_bf16 v[116:119], v[176:179], v[184:187], 0
	v_mfma_f32_16x16x32_bf16 v[104:107], v[148:151], v[196:199], 0
	v_mfma_f32_16x16x32_bf16 v[100:103], v[176:179], v[196:199], 0
	v_mfma_f32_16x16x32_bf16 v[88:91], v[148:151], v[204:207], 0
	v_mfma_f32_16x16x32_bf16 v[84:87], v[176:179], v[204:207], 0
	v_mfma_f32_16x16x32_bf16 v[72:75], v[148:151], v[234:237], 0
	v_mfma_f32_16x16x32_bf16 v[68:71], v[176:179], v[234:237], 0
	v_mfma_f32_16x16x32_bf16 v[120:123], v[152:155], v[188:191], v[120:123]
	v_mfma_f32_16x16x32_bf16 v[116:119], v[180:183], v[188:191], v[116:119]
	v_mfma_f32_16x16x32_bf16 v[104:107], v[152:155], v[200:203], v[104:107]
	v_mfma_f32_16x16x32_bf16 v[100:103], v[180:183], v[200:203], v[100:103]
	v_mfma_f32_16x16x32_bf16 v[88:91], v[152:155], v[208:211], v[88:91]
	v_mfma_f32_16x16x32_bf16 v[84:87], v[180:183], v[208:211], v[84:87]
	v_mfma_f32_16x16x32_bf16 v[72:75], v[152:155], v[238:241], v[72:75]
	v_mfma_f32_16x16x32_bf16 v[68:71], v[180:183], v[238:241], v[68:71]
	s_setprio 0
	s_barrier
	s_add_i32 s62, s62, s52
	v_lshl_add_u64 v[166:167], s[46:47], 0, v[2:3]
	s_mov_b32 m0, s62
	ds_read_b128 v[184:187], v194 offset:16384
	ds_read_b128 v[188:191], v194 offset:17408
	ds_read_b128 v[196:199], v194 offset:18432
	ds_read_b128 v[200:203], v194 offset:19456
	ds_read_b128 v[204:207], v194 offset:20480
	ds_read_b128 v[208:211], v194 offset:21504
	ds_read_b128 v[234:237], v194 offset:22528
	ds_read_b128 v[238:241], v194 offset:23552
	global_load_lds_dwordx4 v[166:167], off
	s_add_i32 m0, s62, 0x2000
	s_add_u32 s62, s46, 0x40000
	v_lshl_add_u64 v[212:213], s[46:47], 0, v[156:157]
	s_addc_u32 s63, s47, 0
	s_add_i32 s64, s64, s52
	global_load_lds_dwordx4 v[212:213], off
	v_lshl_add_u64 v[242:243], s[62:63], 0, v[2:3]
	s_mov_b32 m0, s64
	v_lshl_add_u64 v[244:245], s[48:49], 0, v[158:159]
	global_load_lds_dwordx4 v[242:243], off
	v_lshl_add_u64 v[242:243], s[62:63], 0, v[156:157]
	s_add_i32 m0, s64, 0x2000
	s_nop 0
	global_load_lds_dwordx4 v[242:243], off
	v_lshl_add_u64 v[242:243], s[48:49], 0, v[160:161]
	s_mov_b32 m0, s53
	s_nop 0
	global_load_lds_dwordx4 v[242:243], off
	s_mov_b32 m0, s54
	s_nop 0
	global_load_lds_dwordx4 v[244:245], off
	s_waitcnt vmcnt(8)
	s_waitcnt lgkmcnt(0)
	s_barrier
	s_setprio 1
	s_waitcnt lgkmcnt(0)
	v_mfma_f32_16x16x32_bf16 v[64:67], v[132:135], v[184:187], 0
	v_mfma_f32_16x16x32_bf16 v[60:63], v[140:143], v[184:187], 0
	v_mfma_f32_16x16x32_bf16 v[48:51], v[132:135], v[196:199], 0
	v_mfma_f32_16x16x32_bf16 v[44:47], v[140:143], v[196:199], 0
	v_mfma_f32_16x16x32_bf16 v[32:35], v[132:135], v[204:207], 0
	v_mfma_f32_16x16x32_bf16 v[28:31], v[140:143], v[204:207], 0
	v_mfma_f32_16x16x32_bf16 v[16:19], v[132:135], v[234:237], 0
	v_mfma_f32_16x16x32_bf16 v[12:15], v[140:143], v[234:237], 0
	v_mfma_f32_16x16x32_bf16 v[64:67], v[136:139], v[188:191], v[64:67]
	v_mfma_f32_16x16x32_bf16 v[60:63], v[144:147], v[188:191], v[60:63]
	v_mfma_f32_16x16x32_bf16 v[48:51], v[136:139], v[200:203], v[48:51]
	v_mfma_f32_16x16x32_bf16 v[44:47], v[144:147], v[200:203], v[44:47]
	v_mfma_f32_16x16x32_bf16 v[32:35], v[136:139], v[208:211], v[32:35]
	v_mfma_f32_16x16x32_bf16 v[28:31], v[144:147], v[208:211], v[28:31]
	v_mfma_f32_16x16x32_bf16 v[16:19], v[136:139], v[238:241], v[16:19]
	v_mfma_f32_16x16x32_bf16 v[12:15], v[144:147], v[238:241], v[12:15]
	s_setprio 0
	s_setprio 1
	v_mfma_f32_16x16x32_bf16 v[56:59], v[148:151], v[184:187], 0
	v_mfma_f32_16x16x32_bf16 v[52:55], v[176:179], v[184:187], 0
	v_mfma_f32_16x16x32_bf16 v[40:43], v[148:151], v[196:199], 0
	v_mfma_f32_16x16x32_bf16 v[36:39], v[176:179], v[196:199], 0
	v_mfma_f32_16x16x32_bf16 v[24:27], v[148:151], v[204:207], 0
	v_mfma_f32_16x16x32_bf16 v[20:23], v[176:179], v[204:207], 0
	v_mfma_f32_16x16x32_bf16 v[8:11], v[148:151], v[234:237], 0
	v_mfma_f32_16x16x32_bf16 v[4:7], v[176:179], v[234:237], 0
	v_mfma_f32_16x16x32_bf16 v[56:59], v[152:155], v[188:191], v[56:59]
	v_mfma_f32_16x16x32_bf16 v[52:55], v[180:183], v[188:191], v[52:55]
	v_mfma_f32_16x16x32_bf16 v[40:43], v[152:155], v[200:203], v[40:43]
	v_mfma_f32_16x16x32_bf16 v[36:39], v[180:183], v[200:203], v[36:39]
	v_mfma_f32_16x16x32_bf16 v[24:27], v[152:155], v[208:211], v[24:27]
	v_mfma_f32_16x16x32_bf16 v[20:23], v[180:183], v[208:211], v[20:23]
	v_mfma_f32_16x16x32_bf16 v[8:11], v[152:155], v[238:241], v[8:11]
	v_mfma_f32_16x16x32_bf16 v[4:7], v[180:183], v[238:241], v[4:7]
	s_setprio 0
	s_barrier
	s_add_i32 s62, 0, 0x18000
	s_add_i32 s63, 0, 0x1c000
	v_add_u32_e32 v144, s62, v192
	v_add_u32_e32 v180, s63, v192
	ds_read_b128 v[132:135], v144
	ds_read_b128 v[136:139], v144 offset:1024
	ds_read_b128 v[140:143], v144 offset:2048
	ds_read_b128 v[144:147], v144 offset:3072
	ds_read_b128 v[148:151], v180
	ds_read_b128 v[152:155], v180 offset:1024
	ds_read_b128 v[176:179], v180 offset:2048
	ds_read_b128 v[180:183], v180 offset:3072
	s_add_u32 s48, s48, 0x40000
	s_addc_u32 s49, s49, 0
	s_mov_b32 m0, s55
	v_lshl_add_u64 v[246:247], s[48:49], 0, v[160:161]
	ds_read_b128 v[184:187], v194 offset:32768
	ds_read_b128 v[188:191], v194 offset:33792
	ds_read_b128 v[196:199], v194 offset:34816
	ds_read_b128 v[200:203], v194 offset:35840
	ds_read_b128 v[204:207], v194 offset:36864
	ds_read_b128 v[208:211], v194 offset:37888
	ds_read_b128 v[234:237], v194 offset:38912
	ds_read_b128 v[238:241], v194 offset:39936
	global_load_lds_dwordx4 v[246:247], off
	v_lshl_add_u64 v[246:247], s[48:49], 0, v[158:159]
	s_mov_b32 m0, s56
	s_nop 0
	global_load_lds_dwordx4 v[246:247], off
	s_waitcnt vmcnt(8)
	s_waitcnt lgkmcnt(0)
	s_barrier
	s_setprio 1
	s_waitcnt lgkmcnt(0)
	v_mfma_f32_16x16x32_bf16 v[128:131], v[132:135], v[184:187], v[128:131]
	v_mfma_f32_16x16x32_bf16 v[124:127], v[140:143], v[184:187], v[124:127]
	v_mfma_f32_16x16x32_bf16 v[112:115], v[132:135], v[196:199], v[112:115]
	v_mfma_f32_16x16x32_bf16 v[108:111], v[140:143], v[196:199], v[108:111]
	v_mfma_f32_16x16x32_bf16 v[96:99], v[132:135], v[204:207], v[96:99]
	v_mfma_f32_16x16x32_bf16 v[92:95], v[140:143], v[204:207], v[92:95]
	v_mfma_f32_16x16x32_bf16 v[80:83], v[132:135], v[234:237], v[80:83]
	v_mfma_f32_16x16x32_bf16 v[76:79], v[140:143], v[234:237], v[76:79]
	v_mfma_f32_16x16x32_bf16 v[128:131], v[136:139], v[188:191], v[128:131]
	v_mfma_f32_16x16x32_bf16 v[124:127], v[144:147], v[188:191], v[124:127]
	v_mfma_f32_16x16x32_bf16 v[112:115], v[136:139], v[200:203], v[112:115]
	v_mfma_f32_16x16x32_bf16 v[108:111], v[144:147], v[200:203], v[108:111]
	v_mfma_f32_16x16x32_bf16 v[96:99], v[136:139], v[208:211], v[96:99]
	v_mfma_f32_16x16x32_bf16 v[92:95], v[144:147], v[208:211], v[92:95]
	v_mfma_f32_16x16x32_bf16 v[80:83], v[136:139], v[238:241], v[80:83]
	v_mfma_f32_16x16x32_bf16 v[76:79], v[144:147], v[238:241], v[76:79]
	s_setprio 0
	s_setprio 1
	v_mfma_f32_16x16x32_bf16 v[120:123], v[148:151], v[184:187], v[120:123]
	v_mfma_f32_16x16x32_bf16 v[116:119], v[176:179], v[184:187], v[116:119]
	v_mfma_f32_16x16x32_bf16 v[104:107], v[148:151], v[196:199], v[104:107]
	v_mfma_f32_16x16x32_bf16 v[100:103], v[176:179], v[196:199], v[100:103]
	v_mfma_f32_16x16x32_bf16 v[88:91], v[148:151], v[204:207], v[88:91]
	v_mfma_f32_16x16x32_bf16 v[84:87], v[176:179], v[204:207], v[84:87]
	v_mfma_f32_16x16x32_bf16 v[72:75], v[148:151], v[234:237], v[72:75]
	v_mfma_f32_16x16x32_bf16 v[68:71], v[176:179], v[234:237], v[68:71]
	v_mfma_f32_16x16x32_bf16 v[120:123], v[152:155], v[188:191], v[120:123]
	v_mfma_f32_16x16x32_bf16 v[116:119], v[180:183], v[188:191], v[116:119]
	v_mfma_f32_16x16x32_bf16 v[104:107], v[152:155], v[200:203], v[104:107]
	v_mfma_f32_16x16x32_bf16 v[100:103], v[180:183], v[200:203], v[100:103]
	v_mfma_f32_16x16x32_bf16 v[88:91], v[152:155], v[208:211], v[88:91]
	v_mfma_f32_16x16x32_bf16 v[84:87], v[180:183], v[208:211], v[84:87]
	v_mfma_f32_16x16x32_bf16 v[72:75], v[152:155], v[238:241], v[72:75]
	v_mfma_f32_16x16x32_bf16 v[68:71], v[180:183], v[238:241], v[68:71]
	s_setprio 0
	s_barrier
	s_add_i32 s48, s62, s52
	v_lshl_add_u64 v[166:167], v[166:167], 0, s[16:17]
	s_mov_b32 m0, s48
	ds_read_b128 v[184:187], v194 offset:49152
	ds_read_b128 v[188:191], v194 offset:50176
	ds_read_b128 v[196:199], v194 offset:51200
	ds_read_b128 v[200:203], v194 offset:52224
	ds_read_b128 v[204:207], v194 offset:53248
	ds_read_b128 v[208:211], v194 offset:54272
	ds_read_b128 v[234:237], v194 offset:55296
	ds_read_b128 v[238:241], v194 offset:56320
	global_load_lds_dwordx4 v[166:167], off
	s_add_i32 m0, s48, 0x2000
	s_add_u32 s46, s46, 0x40080
	v_lshl_add_u64 v[166:167], v[212:213], 0, s[16:17]
	s_addc_u32 s47, s47, 0
	s_add_i32 s48, s63, s52
	global_load_lds_dwordx4 v[166:167], off
	v_lshl_add_u64 v[166:167], s[46:47], 0, v[2:3]
	s_mov_b32 m0, s48
	s_nop 0
	global_load_lds_dwordx4 v[166:167], off
	v_lshl_add_u64 v[166:167], s[46:47], 0, v[156:157]
	s_add_i32 m0, s48, 0x2000
	s_nop 0
	global_load_lds_dwordx4 v[166:167], off
	v_lshl_add_u64 v[166:167], v[242:243], 0, s[16:17]
	s_mov_b32 m0, s34
	s_nop 0
	global_load_lds_dwordx4 v[166:167], off
	v_lshl_add_u64 v[166:167], v[244:245], 0, s[16:17]
	s_mov_b32 m0, s57
	s_nop 0
	global_load_lds_dwordx4 v[166:167], off
	s_waitcnt vmcnt(8)
	s_waitcnt lgkmcnt(0)
	s_barrier
	s_setprio 1
	s_waitcnt lgkmcnt(0)
	v_mfma_f32_16x16x32_bf16 v[64:67], v[132:135], v[184:187], v[64:67]
	v_mfma_f32_16x16x32_bf16 v[60:63], v[140:143], v[184:187], v[60:63]
	v_mfma_f32_16x16x32_bf16 v[48:51], v[132:135], v[196:199], v[48:51]
	v_mfma_f32_16x16x32_bf16 v[44:47], v[140:143], v[196:199], v[44:47]
	v_mfma_f32_16x16x32_bf16 v[32:35], v[132:135], v[204:207], v[32:35]
	v_mfma_f32_16x16x32_bf16 v[28:31], v[140:143], v[204:207], v[28:31]
	v_mfma_f32_16x16x32_bf16 v[16:19], v[132:135], v[234:237], v[16:19]
	v_mfma_f32_16x16x32_bf16 v[12:15], v[140:143], v[234:237], v[12:15]
	v_mfma_f32_16x16x32_bf16 v[64:67], v[136:139], v[188:191], v[64:67]
	v_mfma_f32_16x16x32_bf16 v[60:63], v[144:147], v[188:191], v[60:63]
	v_mfma_f32_16x16x32_bf16 v[48:51], v[136:139], v[200:203], v[48:51]
	v_mfma_f32_16x16x32_bf16 v[44:47], v[144:147], v[200:203], v[44:47]
	v_mfma_f32_16x16x32_bf16 v[32:35], v[136:139], v[208:211], v[32:35]
	v_mfma_f32_16x16x32_bf16 v[28:31], v[144:147], v[208:211], v[28:31]
	v_mfma_f32_16x16x32_bf16 v[16:19], v[136:139], v[238:241], v[16:19]
	v_mfma_f32_16x16x32_bf16 v[12:15], v[144:147], v[238:241], v[12:15]
	s_setprio 0
	s_setprio 1
	v_mfma_f32_16x16x32_bf16 v[56:59], v[148:151], v[184:187], v[56:59]
	v_mfma_f32_16x16x32_bf16 v[52:55], v[176:179], v[184:187], v[52:55]
	v_mfma_f32_16x16x32_bf16 v[40:43], v[148:151], v[196:199], v[40:43]
	v_mfma_f32_16x16x32_bf16 v[36:39], v[176:179], v[196:199], v[36:39]
	v_mfma_f32_16x16x32_bf16 v[24:27], v[148:151], v[204:207], v[24:27]
	v_mfma_f32_16x16x32_bf16 v[20:23], v[176:179], v[204:207], v[20:23]
	v_mfma_f32_16x16x32_bf16 v[8:11], v[148:151], v[234:237], v[8:11]
	v_mfma_f32_16x16x32_bf16 v[4:7], v[176:179], v[234:237], v[4:7]
	v_mfma_f32_16x16x32_bf16 v[56:59], v[152:155], v[188:191], v[56:59]
	v_mfma_f32_16x16x32_bf16 v[52:55], v[180:183], v[188:191], v[52:55]
	v_mfma_f32_16x16x32_bf16 v[40:43], v[152:155], v[200:203], v[40:43]
	v_mfma_f32_16x16x32_bf16 v[36:39], v[180:183], v[200:203], v[36:39]
	v_mfma_f32_16x16x32_bf16 v[24:27], v[152:155], v[208:211], v[24:27]
	v_mfma_f32_16x16x32_bf16 v[20:23], v[180:183], v[208:211], v[20:23]
	v_mfma_f32_16x16x32_bf16 v[8:11], v[152:155], v[238:241], v[8:11]
	v_mfma_f32_16x16x32_bf16 v[4:7], v[180:183], v[238:241], v[4:7]
	s_setprio 0
	s_barrier
	s_add_i32 s61, s61, 2
	s_add_u32 s30, s30, 0x100
	s_addc_u32 s31, s31, 0
	s_add_u32 s59, s59, 0x100
	s_addc_u32 s60, s60, 0
	s_cmp_gt_u32 s61, 13

.LBB0_862:
	s_ashr_i32 s31, s30, 31
	s_lshl_b64 s[44:45], s[30:31], 19
	s_add_u32 s44, s11, s44
	s_addc_u32 s45, s14, s45
	s_and_b64 s[46:47], s[42:43], exec
	s_cselect_b32 s31, s45, s5
	s_cselect_b32 s60, s44, s4
	s_ashr_i32 s29, s28, 31
	s_lshl_b64 s[46:47], s[28:29], 19
	s_add_u32 s46, s15, s46
	s_addc_u32 s47, s50, s47
	s_and_b64 s[48:49], s[42:43], exec
	s_cselect_b32 s29, s47, s19
	s_cselect_b32 s61, s46, s18
	s_add_u32 s4, s4, 0x40080
	s_addc_u32 s5, s5, 0
	s_add_u32 s62, s18, 0x100
	s_addc_u32 s63, s19, 0
	s_mov_b32 s64, -2
	s_add_u32 s18, s4, 0xfffc0080
	s_addc_u32 s19, s5, -1
	s_add_i32 s65, 0, 0x10000
	s_cmp_eq_u32 s64, 12
	s_cselect_b32 s49, s31, s19
	s_cselect_b32 s48, s60, s18
	v_add_u32_e32 v146, s65, v147
	s_cselect_b32 s19, s29, s63
	s_cselect_b32 s18, s61, s62
	s_add_i32 s68, 0, 0x14000
	ds_read_b128 v[132:135], v146
	ds_read_b128 v[152:155], v146 offset:1024
	ds_read_b128 v[156:159], v146 offset:2048
	ds_read_b128 v[160:163], v146 offset:3072
	v_add_u32_e32 v146, s68, v147
	ds_read_b128 v[164:167], v146
	ds_read_b128 v[176:179], v146 offset:1024
	ds_read_b128 v[180:183], v146 offset:2048
	ds_read_b128 v[184:187], v146 offset:3072
	v_lshl_add_u64 v[212:213], s[4:5], 0, v[142:143]
	s_add_i32 m0, s52, 0xc000
	ds_read_b128 v[188:191], v151
	ds_read_b128 v[192:195], v151 offset:1024
	ds_read_b128 v[196:199], v151 offset:2048
	ds_read_b128 v[200:203], v151 offset:3072
	ds_read_b128 v[204:207], v151 offset:4096
	ds_read_b128 v[208:211], v151 offset:5120
	ds_read_b128 v[234:237], v151 offset:6144
	ds_read_b128 v[238:241], v151 offset:7168
	global_load_lds_dwordx4 v[212:213], off
	v_lshl_add_u64 v[212:213], s[4:5], 0, v[144:145]
	s_add_i32 m0, s52, 0xe000
	s_nop 0
	global_load_lds_dwordx4 v[212:213], off
	s_waitcnt vmcnt(8)
	s_waitcnt lgkmcnt(0)
	s_barrier
	s_setprio 1
	s_waitcnt lgkmcnt(0)
	v_mfma_f32_16x16x32_bf16 v[128:131], v[132:135], v[188:191], 0
	v_mfma_f32_16x16x32_bf16 v[124:127], v[156:159], v[188:191], 0
	v_mfma_f32_16x16x32_bf16 v[112:115], v[132:135], v[196:199], 0
	v_mfma_f32_16x16x32_bf16 v[108:111], v[156:159], v[196:199], 0
	v_mfma_f32_16x16x32_bf16 v[96:99], v[132:135], v[204:207], 0
	v_mfma_f32_16x16x32_bf16 v[92:95], v[156:159], v[204:207], 0
	v_mfma_f32_16x16x32_bf16 v[80:83], v[132:135], v[234:237], 0
	v_mfma_f32_16x16x32_bf16 v[76:79], v[156:159], v[234:237], 0
	v_mfma_f32_16x16x32_bf16 v[128:131], v[152:155], v[192:195], v[128:131]
	v_mfma_f32_16x16x32_bf16 v[124:127], v[160:163], v[192:195], v[124:127]
	v_mfma_f32_16x16x32_bf16 v[112:115], v[152:155], v[200:203], v[112:115]
	v_mfma_f32_16x16x32_bf16 v[108:111], v[160:163], v[200:203], v[108:111]
	v_mfma_f32_16x16x32_bf16 v[96:99], v[152:155], v[208:211], v[96:99]
	v_mfma_f32_16x16x32_bf16 v[92:95], v[160:163], v[208:211], v[92:95]
	v_mfma_f32_16x16x32_bf16 v[80:83], v[152:155], v[238:241], v[80:83]
	v_mfma_f32_16x16x32_bf16 v[76:79], v[160:163], v[238:241], v[76:79]
	s_setprio 0
	s_setprio 1
	v_mfma_f32_16x16x32_bf16 v[120:123], v[164:167], v[188:191], 0
	v_mfma_f32_16x16x32_bf16 v[116:119], v[180:183], v[188:191], 0
	v_mfma_f32_16x16x32_bf16 v[104:107], v[164:167], v[196:199], 0
	v_mfma_f32_16x16x32_bf16 v[100:103], v[180:183], v[196:199], 0
	v_mfma_f32_16x16x32_bf16 v[88:91], v[164:167], v[204:207], 0
	v_mfma_f32_16x16x32_bf16 v[84:87], v[180:183], v[204:207], 0
	v_mfma_f32_16x16x32_bf16 v[72:75], v[164:167], v[234:237], 0
	v_mfma_f32_16x16x32_bf16 v[68:71], v[180:183], v[234:237], 0
	v_mfma_f32_16x16x32_bf16 v[120:123], v[176:179], v[192:195], v[120:123]
	v_mfma_f32_16x16x32_bf16 v[116:119], v[184:187], v[192:195], v[116:119]
	v_mfma_f32_16x16x32_bf16 v[104:107], v[176:179], v[200:203], v[104:107]
	v_mfma_f32_16x16x32_bf16 v[100:103], v[184:187], v[200:203], v[100:103]
	v_mfma_f32_16x16x32_bf16 v[88:91], v[176:179], v[208:211], v[88:91]
	v_mfma_f32_16x16x32_bf16 v[84:87], v[184:187], v[208:211], v[84:87]
	v_mfma_f32_16x16x32_bf16 v[72:75], v[176:179], v[238:241], v[72:75]
	v_mfma_f32_16x16x32_bf16 v[68:71], v[184:187], v[238:241], v[68:71]
	s_setprio 0
	s_barrier
	s_add_i32 s65, s65, s51
	v_lshl_add_u64 v[212:213], s[18:19], 0, v[2:3]
	s_mov_b32 m0, s65
	ds_read_b128 v[188:191], v151 offset:16384
	ds_read_b128 v[192:195], v151 offset:17408
	ds_read_b128 v[196:199], v151 offset:18432
	ds_read_b128 v[200:203], v151 offset:19456
	ds_read_b128 v[204:207], v151 offset:20480
	ds_read_b128 v[208:211], v151 offset:21504
	ds_read_b128 v[234:237], v151 offset:22528
	ds_read_b128 v[238:241], v151 offset:23552
	global_load_lds_dwordx4 v[212:213], off
	s_add_i32 m0, s65, 0x2000
	s_add_u32 s66, s18, 0x40000
	v_lshl_add_u64 v[242:243], s[18:19], 0, v[136:137]
	s_addc_u32 s67, s19, 0
	s_add_i32 s65, s68, s51
	global_load_lds_dwordx4 v[242:243], off
	v_lshl_add_u64 v[244:245], s[66:67], 0, v[2:3]
	s_mov_b32 m0, s65
	v_lshl_add_u64 v[246:247], s[48:49], 0, v[138:139]
	global_load_lds_dwordx4 v[244:245], off
	v_lshl_add_u64 v[244:245], s[66:67], 0, v[136:137]
	s_add_i32 m0, s65, 0x2000
	s_nop 0
	global_load_lds_dwordx4 v[244:245], off
	v_lshl_add_u64 v[244:245], s[48:49], 0, v[140:141]
	s_mov_b32 m0, s52
	s_nop 0
	global_load_lds_dwordx4 v[244:245], off
	s_mov_b32 m0, s53
	s_nop 0
	global_load_lds_dwordx4 v[246:247], off
	s_waitcnt vmcnt(8)
	s_waitcnt lgkmcnt(0)
	s_barrier
	s_setprio 1
	s_waitcnt lgkmcnt(0)
	v_mfma_f32_16x16x32_bf16 v[64:67], v[132:135], v[188:191], 0
	v_mfma_f32_16x16x32_bf16 v[60:63], v[156:159], v[188:191], 0
	v_mfma_f32_16x16x32_bf16 v[48:51], v[132:135], v[196:199], 0
	v_mfma_f32_16x16x32_bf16 v[44:47], v[156:159], v[196:199], 0
	v_mfma_f32_16x16x32_bf16 v[32:35], v[132:135], v[204:207], 0
	v_mfma_f32_16x16x32_bf16 v[28:31], v[156:159], v[204:207], 0
	v_mfma_f32_16x16x32_bf16 v[16:19], v[132:135], v[234:237], 0
	v_mfma_f32_16x16x32_bf16 v[12:15], v[156:159], v[234:237], 0
	v_mfma_f32_16x16x32_bf16 v[64:67], v[152:155], v[192:195], v[64:67]
	v_mfma_f32_16x16x32_bf16 v[60:63], v[160:163], v[192:195], v[60:63]
	v_mfma_f32_16x16x32_bf16 v[48:51], v[152:155], v[200:203], v[48:51]
	v_mfma_f32_16x16x32_bf16 v[44:47], v[160:163], v[200:203], v[44:47]
	v_mfma_f32_16x16x32_bf16 v[32:35], v[152:155], v[208:211], v[32:35]
	v_mfma_f32_16x16x32_bf16 v[28:31], v[160:163], v[208:211], v[28:31]
	v_mfma_f32_16x16x32_bf16 v[16:19], v[152:155], v[238:241], v[16:19]
	v_mfma_f32_16x16x32_bf16 v[12:15], v[160:163], v[238:241], v[12:15]
	s_setprio 0
	s_setprio 1
	v_mfma_f32_16x16x32_bf16 v[56:59], v[164:167], v[188:191], 0
	v_mfma_f32_16x16x32_bf16 v[52:55], v[180:183], v[188:191], 0
	v_mfma_f32_16x16x32_bf16 v[40:43], v[164:167], v[196:199], 0
	v_mfma_f32_16x16x32_bf16 v[36:39], v[180:183], v[196:199], 0
	v_mfma_f32_16x16x32_bf16 v[24:27], v[164:167], v[204:207], 0
	v_mfma_f32_16x16x32_bf16 v[20:23], v[180:183], v[204:207], 0
	v_mfma_f32_16x16x32_bf16 v[8:11], v[164:167], v[234:237], 0
	v_mfma_f32_16x16x32_bf16 v[4:7], v[180:183], v[234:237], 0
	v_mfma_f32_16x16x32_bf16 v[56:59], v[176:179], v[192:195], v[56:59]
	v_mfma_f32_16x16x32_bf16 v[52:55], v[184:187], v[192:195], v[52:55]
	v_mfma_f32_16x16x32_bf16 v[40:43], v[176:179], v[200:203], v[40:43]
	v_mfma_f32_16x16x32_bf16 v[36:39], v[184:187], v[200:203], v[36:39]
	v_mfma_f32_16x16x32_bf16 v[24:27], v[176:179], v[208:211], v[24:27]
	v_mfma_f32_16x16x32_bf16 v[20:23], v[184:187], v[208:211], v[20:23]
	v_mfma_f32_16x16x32_bf16 v[8:11], v[176:179], v[238:241], v[8:11]
	v_mfma_f32_16x16x32_bf16 v[4:7], v[184:187], v[238:241], v[4:7]
	s_setprio 0
	s_barrier
	s_add_i32 s65, 0, 0x18000
	v_add_u32_e32 v146, s65, v147
	s_add_i32 s66, 0, 0x1c000
	ds_read_b128 v[132:135], v146
	ds_read_b128 v[152:155], v146 offset:1024
	ds_read_b128 v[156:159], v146 offset:2048
	ds_read_b128 v[160:163], v146 offset:3072
	v_add_u32_e32 v146, s66, v147
	ds_read_b128 v[164:167], v146
	ds_read_b128 v[176:179], v146 offset:1024
	ds_read_b128 v[180:183], v146 offset:2048
	ds_read_b128 v[184:187], v146 offset:3072
	s_add_u32 s48, s48, 0x40000
	s_addc_u32 s49, s49, 0
	s_mov_b32 m0, s54
	v_lshl_add_u64 v[248:249], s[48:49], 0, v[140:141]
	ds_read_b128 v[188:191], v151 offset:32768
	ds_read_b128 v[192:195], v151 offset:33792
	ds_read_b128 v[196:199], v151 offset:34816
	ds_read_b128 v[200:203], v151 offset:35840
	ds_read_b128 v[204:207], v151 offset:36864
	ds_read_b128 v[208:211], v151 offset:37888
	ds_read_b128 v[234:237], v151 offset:38912
	ds_read_b128 v[238:241], v151 offset:39936
	global_load_lds_dwordx4 v[248:249], off
	v_lshl_add_u64 v[248:249], s[48:49], 0, v[138:139]
	s_mov_b32 m0, s55
	s_nop 0
	global_load_lds_dwordx4 v[248:249], off
	s_waitcnt vmcnt(8)
	s_waitcnt lgkmcnt(0)
	s_barrier
	s_setprio 1
	s_waitcnt lgkmcnt(0)
	v_mfma_f32_16x16x32_bf16 v[128:131], v[132:135], v[188:191], v[128:131]
	v_mfma_f32_16x16x32_bf16 v[124:127], v[156:159], v[188:191], v[124:127]
	v_mfma_f32_16x16x32_bf16 v[112:115], v[132:135], v[196:199], v[112:115]
	v_mfma_f32_16x16x32_bf16 v[108:111], v[156:159], v[196:199], v[108:111]
	v_mfma_f32_16x16x32_bf16 v[96:99], v[132:135], v[204:207], v[96:99]
	v_mfma_f32_16x16x32_bf16 v[92:95], v[156:159], v[204:207], v[92:95]
	v_mfma_f32_16x16x32_bf16 v[80:83], v[132:135], v[234:237], v[80:83]
	v_mfma_f32_16x16x32_bf16 v[76:79], v[156:159], v[234:237], v[76:79]
	v_mfma_f32_16x16x32_bf16 v[128:131], v[152:155], v[192:195], v[128:131]
	v_mfma_f32_16x16x32_bf16 v[124:127], v[160:163], v[192:195], v[124:127]
	v_mfma_f32_16x16x32_bf16 v[112:115], v[152:155], v[200:203], v[112:115]
	v_mfma_f32_16x16x32_bf16 v[108:111], v[160:163], v[200:203], v[108:111]
	v_mfma_f32_16x16x32_bf16 v[96:99], v[152:155], v[208:211], v[96:99]
	v_mfma_f32_16x16x32_bf16 v[92:95], v[160:163], v[208:211], v[92:95]
	v_mfma_f32_16x16x32_bf16 v[80:83], v[152:155], v[238:241], v[80:83]
	v_mfma_f32_16x16x32_bf16 v[76:79], v[160:163], v[238:241], v[76:79]
	s_setprio 0
	s_setprio 1
	v_mfma_f32_16x16x32_bf16 v[120:123], v[164:167], v[188:191], v[120:123]
	v_mfma_f32_16x16x32_bf16 v[116:119], v[180:183], v[188:191], v[116:119]
	v_mfma_f32_16x16x32_bf16 v[104:107], v[164:167], v[196:199], v[104:107]
	v_mfma_f32_16x16x32_bf16 v[100:103], v[180:183], v[196:199], v[100:103]
	v_mfma_f32_16x16x32_bf16 v[88:91], v[164:167], v[204:207], v[88:91]
	v_mfma_f32_16x16x32_bf16 v[84:87], v[180:183], v[204:207], v[84:87]
	v_mfma_f32_16x16x32_bf16 v[72:75], v[164:167], v[234:237], v[72:75]
	v_mfma_f32_16x16x32_bf16 v[68:71], v[180:183], v[234:237], v[68:71]
	v_mfma_f32_16x16x32_bf16 v[120:123], v[176:179], v[192:195], v[120:123]
	v_mfma_f32_16x16x32_bf16 v[116:119], v[184:187], v[192:195], v[116:119]
	v_mfma_f32_16x16x32_bf16 v[104:107], v[176:179], v[200:203], v[104:107]
	v_mfma_f32_16x16x32_bf16 v[100:103], v[184:187], v[200:203], v[100:103]
	v_mfma_f32_16x16x32_bf16 v[88:91], v[176:179], v[208:211], v[88:91]
	v_mfma_f32_16x16x32_bf16 v[84:87], v[184:187], v[208:211], v[84:87]
	v_mfma_f32_16x16x32_bf16 v[72:75], v[176:179], v[238:241], v[72:75]
	v_mfma_f32_16x16x32_bf16 v[68:71], v[184:187], v[238:241], v[68:71]
	s_setprio 0
	s_barrier
	s_add_i32 s48, s65, s51
	v_lshl_add_u64 v[212:213], v[212:213], 0, s[16:17]
	s_mov_b32 m0, s48
	ds_read_b128 v[188:191], v151 offset:49152
	ds_read_b128 v[192:195], v151 offset:50176
	ds_read_b128 v[196:199], v151 offset:51200
	ds_read_b128 v[200:203], v151 offset:52224
	ds_read_b128 v[204:207], v151 offset:53248
	ds_read_b128 v[208:211], v151 offset:54272
	ds_read_b128 v[234:237], v151 offset:55296
	ds_read_b128 v[238:241], v151 offset:56320
	global_load_lds_dwordx4 v[212:213], off
	s_add_i32 m0, s48, 0x2000
	s_add_u32 s18, s18, 0x40080
	v_lshl_add_u64 v[212:213], v[242:243], 0, s[16:17]
	s_addc_u32 s19, s19, 0
	s_add_i32 s48, s66, s51
	global_load_lds_dwordx4 v[212:213], off
	v_lshl_add_u64 v[212:213], s[18:19], 0, v[2:3]
	s_mov_b32 m0, s48
	s_nop 0
	global_load_lds_dwordx4 v[212:213], off
	v_lshl_add_u64 v[212:213], s[18:19], 0, v[136:137]
	s_add_i32 m0, s48, 0x2000
	s_nop 0
	global_load_lds_dwordx4 v[212:213], off
	v_lshl_add_u64 v[212:213], v[244:245], 0, s[16:17]
	s_mov_b32 m0, s34
	s_nop 0
	global_load_lds_dwordx4 v[212:213], off
	v_lshl_add_u64 v[212:213], v[246:247], 0, s[16:17]
	s_mov_b32 m0, s56
	s_nop 0
	global_load_lds_dwordx4 v[212:213], off
	s_waitcnt vmcnt(8)
	s_waitcnt lgkmcnt(0)
	s_barrier
	s_setprio 1
	s_waitcnt lgkmcnt(0)
	v_mfma_f32_16x16x32_bf16 v[64:67], v[132:135], v[188:191], v[64:67]
	v_mfma_f32_16x16x32_bf16 v[60:63], v[156:159], v[188:191], v[60:63]
	v_mfma_f32_16x16x32_bf16 v[48:51], v[132:135], v[196:199], v[48:51]
	v_mfma_f32_16x16x32_bf16 v[44:47], v[156:159], v[196:199], v[44:47]
	v_mfma_f32_16x16x32_bf16 v[32:35], v[132:135], v[204:207], v[32:35]
	v_mfma_f32_16x16x32_bf16 v[28:31], v[156:159], v[204:207], v[28:31]
	v_mfma_f32_16x16x32_bf16 v[16:19], v[132:135], v[234:237], v[16:19]
	v_mfma_f32_16x16x32_bf16 v[12:15], v[156:159], v[234:237], v[12:15]
	v_mfma_f32_16x16x32_bf16 v[64:67], v[152:155], v[192:195], v[64:67]
	v_mfma_f32_16x16x32_bf16 v[60:63], v[160:163], v[192:195], v[60:63]
	v_mfma_f32_16x16x32_bf16 v[48:51], v[152:155], v[200:203], v[48:51]
	v_mfma_f32_16x16x32_bf16 v[44:47], v[160:163], v[200:203], v[44:47]
	v_mfma_f32_16x16x32_bf16 v[32:35], v[152:155], v[208:211], v[32:35]
	v_mfma_f32_16x16x32_bf16 v[28:31], v[160:163], v[208:211], v[28:31]
	v_mfma_f32_16x16x32_bf16 v[16:19], v[152:155], v[238:241], v[16:19]
	v_mfma_f32_16x16x32_bf16 v[12:15], v[160:163], v[238:241], v[12:15]
	s_setprio 0
	s_setprio 1
	v_mfma_f32_16x16x32_bf16 v[56:59], v[164:167], v[188:191], v[56:59]
	v_mfma_f32_16x16x32_bf16 v[52:55], v[180:183], v[188:191], v[52:55]
	v_mfma_f32_16x16x32_bf16 v[40:43], v[164:167], v[196:199], v[40:43]
	v_mfma_f32_16x16x32_bf16 v[36:39], v[180:183], v[196:199], v[36:39]
	v_mfma_f32_16x16x32_bf16 v[24:27], v[164:167], v[204:207], v[24:27]
	v_mfma_f32_16x16x32_bf16 v[20:23], v[180:183], v[204:207], v[20:23]
	v_mfma_f32_16x16x32_bf16 v[8:11], v[164:167], v[234:237], v[8:11]
	v_mfma_f32_16x16x32_bf16 v[4:7], v[180:183], v[234:237], v[4:7]
	v_mfma_f32_16x16x32_bf16 v[56:59], v[176:179], v[192:195], v[56:59]
	v_mfma_f32_16x16x32_bf16 v[52:55], v[184:187], v[192:195], v[52:55]
	v_mfma_f32_16x16x32_bf16 v[40:43], v[176:179], v[200:203], v[40:43]
	v_mfma_f32_16x16x32_bf16 v[36:39], v[184:187], v[200:203], v[36:39]
	v_mfma_f32_16x16x32_bf16 v[24:27], v[176:179], v[208:211], v[24:27]
	v_mfma_f32_16x16x32_bf16 v[20:23], v[184:187], v[208:211], v[20:23]
	v_mfma_f32_16x16x32_bf16 v[8:11], v[176:179], v[238:241], v[8:11]
	v_mfma_f32_16x16x32_bf16 v[4:7], v[184:187], v[238:241], v[4:7]
	s_setprio 0
	s_barrier
	s_add_i32 s64, s64, 2
	s_add_u32 s4, s4, 0x100
	s_addc_u32 s5, s5, 0
	s_add_u32 s62, s62, 0x100
	s_addc_u32 s63, s63, 0
	s_cmp_gt_u32 s64, 13

.LBB0_998:
	s_add_u32 s14, s18, 0x100
	s_addc_u32 s15, s19, 0
	s_mov_b32 s69, -2
	s_waitcnt lgkmcnt(0)
	s_add_u32 s4, s6, 0x100
	s_addc_u32 s5, s7, 0
	s_add_i32 s70, 0, 0x10000
	s_cmp_eq_u32 s69, 40
	s_cselect_b32 s55, s51, s5
	s_cselect_b32 s54, s50, s4
	s_cselect_b32 s19, s53, s15
	s_cselect_b32 s18, s52, s14
	s_add_i32 s71, 0, 0x14000
	v_add_u32_e32 v144, s70, v194
	v_add_u32_e32 v178, s71, v194
	ds_read_b128 v[132:135], v144
	ds_read_b128 v[136:139], v144 offset:1024
	ds_read_b128 v[140:143], v144 offset:2048
	ds_read_b128 v[144:147], v144 offset:3072
	ds_read_b128 v[148:151], v178
	ds_read_b128 v[152:155], v178 offset:1024
	ds_read_b128 v[156:159], v178 offset:2048
	ds_read_b128 v[178:181], v178 offset:3072
	v_lshl_add_u64 v[238:239], s[6:7], 0, v[166:167]
	s_add_i32 m0, s61, 0xc000
	ds_read_b128 v[182:185], v196
	ds_read_b128 v[186:189], v196 offset:1024
	ds_read_b128 v[190:193], v196 offset:2048
	ds_read_b128 v[198:201], v196 offset:3072
	ds_read_b128 v[202:205], v196 offset:4096
	ds_read_b128 v[206:209], v196 offset:5120
	ds_read_b128 v[210:213], v196 offset:6144
	ds_read_b128 v[234:237], v196 offset:7168
	global_load_lds_dwordx4 v[238:239], off
	v_lshl_add_u64 v[238:239], s[6:7], 0, v[176:177]
	s_add_i32 m0, s61, 0xe000
	s_nop 0
	global_load_lds_dwordx4 v[238:239], off
	s_waitcnt vmcnt(8)
	s_waitcnt lgkmcnt(0)
	s_barrier
	s_setprio 1
	s_waitcnt lgkmcnt(0)
	v_mfma_f32_16x16x32_bf16 v[128:131], v[132:135], v[182:185], 0
	v_mfma_f32_16x16x32_bf16 v[124:127], v[140:143], v[182:185], 0
	v_mfma_f32_16x16x32_bf16 v[112:115], v[132:135], v[190:193], 0
	v_mfma_f32_16x16x32_bf16 v[108:111], v[140:143], v[190:193], 0
	v_mfma_f32_16x16x32_bf16 v[96:99], v[132:135], v[202:205], 0
	v_mfma_f32_16x16x32_bf16 v[92:95], v[140:143], v[202:205], 0
	v_mfma_f32_16x16x32_bf16 v[80:83], v[132:135], v[210:213], 0
	v_mfma_f32_16x16x32_bf16 v[76:79], v[140:143], v[210:213], 0
	v_mfma_f32_16x16x32_bf16 v[128:131], v[136:139], v[186:189], v[128:131]
	v_mfma_f32_16x16x32_bf16 v[124:127], v[144:147], v[186:189], v[124:127]
	v_mfma_f32_16x16x32_bf16 v[112:115], v[136:139], v[198:201], v[112:115]
	v_mfma_f32_16x16x32_bf16 v[108:111], v[144:147], v[198:201], v[108:111]
	v_mfma_f32_16x16x32_bf16 v[96:99], v[136:139], v[206:209], v[96:99]
	v_mfma_f32_16x16x32_bf16 v[92:95], v[144:147], v[206:209], v[92:95]
	v_mfma_f32_16x16x32_bf16 v[80:83], v[136:139], v[234:237], v[80:83]
	v_mfma_f32_16x16x32_bf16 v[76:79], v[144:147], v[234:237], v[76:79]
	s_setprio 0
	s_setprio 1
	v_mfma_f32_16x16x32_bf16 v[120:123], v[148:151], v[182:185], 0
	v_mfma_f32_16x16x32_bf16 v[116:119], v[156:159], v[182:185], 0
	v_mfma_f32_16x16x32_bf16 v[104:107], v[148:151], v[190:193], 0
	v_mfma_f32_16x16x32_bf16 v[100:103], v[156:159], v[190:193], 0
	v_mfma_f32_16x16x32_bf16 v[88:91], v[148:151], v[202:205], 0
	v_mfma_f32_16x16x32_bf16 v[84:87], v[156:159], v[202:205], 0
	v_mfma_f32_16x16x32_bf16 v[72:75], v[148:151], v[210:213], 0
	v_mfma_f32_16x16x32_bf16 v[68:71], v[156:159], v[210:213], 0
	v_mfma_f32_16x16x32_bf16 v[120:123], v[152:155], v[186:189], v[120:123]
	v_mfma_f32_16x16x32_bf16 v[116:119], v[178:181], v[186:189], v[116:119]
	v_mfma_f32_16x16x32_bf16 v[104:107], v[152:155], v[198:201], v[104:107]
	v_mfma_f32_16x16x32_bf16 v[100:103], v[178:181], v[198:201], v[100:103]
	v_mfma_f32_16x16x32_bf16 v[88:91], v[152:155], v[206:209], v[88:91]
	v_mfma_f32_16x16x32_bf16 v[84:87], v[178:181], v[206:209], v[84:87]
	v_mfma_f32_16x16x32_bf16 v[72:75], v[152:155], v[234:237], v[72:75]
	v_mfma_f32_16x16x32_bf16 v[68:71], v[178:181], v[234:237], v[68:71]
	s_setprio 0
	s_barrier
	s_add_i32 s6, s70, s56
	v_lshl_add_u64 v[238:239], s[18:19], 0, v[2:3]
	s_mov_b32 m0, s6
	ds_read_b128 v[182:185], v196 offset:16384
	ds_read_b128 v[186:189], v196 offset:17408
	ds_read_b128 v[190:193], v196 offset:18432
	ds_read_b128 v[198:201], v196 offset:19456
	ds_read_b128 v[202:205], v196 offset:20480
	ds_read_b128 v[206:209], v196 offset:21504
	ds_read_b128 v[210:213], v196 offset:22528
	ds_read_b128 v[234:237], v196 offset:23552
	global_load_lds_dwordx4 v[238:239], off
	s_add_i32 m0, s6, 0x2000
	s_add_u32 s6, s18, 0xb0000
	v_lshl_add_u64 v[240:241], s[18:19], 0, v[160:161]
	s_addc_u32 s7, s19, 0
	s_add_i32 s70, s71, s56
	global_load_lds_dwordx4 v[240:241], off
	v_lshl_add_u64 v[242:243], s[6:7], 0, v[2:3]
	s_mov_b32 m0, s70
	v_lshl_add_u64 v[244:245], s[54:55], 0, v[162:163]
	global_load_lds_dwordx4 v[242:243], off
	v_lshl_add_u64 v[242:243], s[6:7], 0, v[160:161]
	s_add_i32 m0, s70, 0x2000
	s_nop 0
	global_load_lds_dwordx4 v[242:243], off
	v_lshl_add_u64 v[242:243], s[54:55], 0, v[164:165]
	s_mov_b32 m0, s61
	s_nop 0
	global_load_lds_dwordx4 v[242:243], off
	s_mov_b32 m0, s62
	s_nop 0
	global_load_lds_dwordx4 v[244:245], off
	s_waitcnt vmcnt(8)
	s_waitcnt lgkmcnt(0)
	s_barrier
	s_setprio 1
	s_waitcnt lgkmcnt(0)
	v_mfma_f32_16x16x32_bf16 v[64:67], v[132:135], v[182:185], 0
	v_mfma_f32_16x16x32_bf16 v[60:63], v[140:143], v[182:185], 0
	v_mfma_f32_16x16x32_bf16 v[48:51], v[132:135], v[190:193], 0
	v_mfma_f32_16x16x32_bf16 v[44:47], v[140:143], v[190:193], 0
	v_mfma_f32_16x16x32_bf16 v[32:35], v[132:135], v[202:205], 0
	v_mfma_f32_16x16x32_bf16 v[28:31], v[140:143], v[202:205], 0
	v_mfma_f32_16x16x32_bf16 v[16:19], v[132:135], v[210:213], 0
	v_mfma_f32_16x16x32_bf16 v[12:15], v[140:143], v[210:213], 0
	v_mfma_f32_16x16x32_bf16 v[64:67], v[136:139], v[186:189], v[64:67]
	v_mfma_f32_16x16x32_bf16 v[60:63], v[144:147], v[186:189], v[60:63]
	v_mfma_f32_16x16x32_bf16 v[48:51], v[136:139], v[198:201], v[48:51]
	v_mfma_f32_16x16x32_bf16 v[44:47], v[144:147], v[198:201], v[44:47]
	v_mfma_f32_16x16x32_bf16 v[32:35], v[136:139], v[206:209], v[32:35]
	v_mfma_f32_16x16x32_bf16 v[28:31], v[144:147], v[206:209], v[28:31]
	v_mfma_f32_16x16x32_bf16 v[16:19], v[136:139], v[234:237], v[16:19]
	v_mfma_f32_16x16x32_bf16 v[12:15], v[144:147], v[234:237], v[12:15]
	s_setprio 0
	s_setprio 1
	v_mfma_f32_16x16x32_bf16 v[56:59], v[148:151], v[182:185], 0
	v_mfma_f32_16x16x32_bf16 v[52:55], v[156:159], v[182:185], 0
	v_mfma_f32_16x16x32_bf16 v[40:43], v[148:151], v[190:193], 0
	v_mfma_f32_16x16x32_bf16 v[36:39], v[156:159], v[190:193], 0
	v_mfma_f32_16x16x32_bf16 v[24:27], v[148:151], v[202:205], 0
	v_mfma_f32_16x16x32_bf16 v[20:23], v[156:159], v[202:205], 0
	v_mfma_f32_16x16x32_bf16 v[8:11], v[148:151], v[210:213], 0
	v_mfma_f32_16x16x32_bf16 v[4:7], v[156:159], v[210:213], 0
	v_mfma_f32_16x16x32_bf16 v[56:59], v[152:155], v[186:189], v[56:59]
	v_mfma_f32_16x16x32_bf16 v[52:55], v[178:181], v[186:189], v[52:55]
	v_mfma_f32_16x16x32_bf16 v[40:43], v[152:155], v[198:201], v[40:43]
	v_mfma_f32_16x16x32_bf16 v[36:39], v[178:181], v[198:201], v[36:39]
	v_mfma_f32_16x16x32_bf16 v[24:27], v[152:155], v[206:209], v[24:27]
	v_mfma_f32_16x16x32_bf16 v[20:23], v[178:181], v[206:209], v[20:23]
	v_mfma_f32_16x16x32_bf16 v[8:11], v[152:155], v[234:237], v[8:11]
	v_mfma_f32_16x16x32_bf16 v[4:7], v[178:181], v[234:237], v[4:7]
	s_setprio 0
	s_barrier
	s_add_i32 s70, 0, 0x18000
	s_add_i32 s71, 0, 0x1c000
	v_add_u32_e32 v144, s70, v194
	v_add_u32_e32 v178, s71, v194
	ds_read_b128 v[132:135], v144
	ds_read_b128 v[136:139], v144 offset:1024
	ds_read_b128 v[140:143], v144 offset:2048
	ds_read_b128 v[144:147], v144 offset:3072
	ds_read_b128 v[148:151], v178
	ds_read_b128 v[152:155], v178 offset:1024
	ds_read_b128 v[156:159], v178 offset:2048
	ds_read_b128 v[178:181], v178 offset:3072
	s_add_u32 s6, s54, 0xb0000
	s_addc_u32 s7, s55, 0
	s_mov_b32 m0, s63
	v_lshl_add_u64 v[246:247], s[6:7], 0, v[164:165]
	ds_read_b128 v[182:185], v196 offset:32768
	ds_read_b128 v[186:189], v196 offset:33792
	ds_read_b128 v[190:193], v196 offset:34816
	ds_read_b128 v[198:201], v196 offset:35840
	ds_read_b128 v[202:205], v196 offset:36864
	ds_read_b128 v[206:209], v196 offset:37888
	ds_read_b128 v[210:213], v196 offset:38912
	ds_read_b128 v[234:237], v196 offset:39936
	global_load_lds_dwordx4 v[246:247], off
	v_lshl_add_u64 v[246:247], s[6:7], 0, v[162:163]
	s_mov_b32 m0, s64
	s_nop 0
	global_load_lds_dwordx4 v[246:247], off
	s_waitcnt vmcnt(8)
	s_waitcnt lgkmcnt(0)
	s_barrier
	s_setprio 1
	s_waitcnt lgkmcnt(0)
	v_mfma_f32_16x16x32_bf16 v[128:131], v[132:135], v[182:185], v[128:131]
	v_mfma_f32_16x16x32_bf16 v[124:127], v[140:143], v[182:185], v[124:127]
	v_mfma_f32_16x16x32_bf16 v[112:115], v[132:135], v[190:193], v[112:115]
	v_mfma_f32_16x16x32_bf16 v[108:111], v[140:143], v[190:193], v[108:111]
	v_mfma_f32_16x16x32_bf16 v[96:99], v[132:135], v[202:205], v[96:99]
	v_mfma_f32_16x16x32_bf16 v[92:95], v[140:143], v[202:205], v[92:95]
	v_mfma_f32_16x16x32_bf16 v[80:83], v[132:135], v[210:213], v[80:83]
	v_mfma_f32_16x16x32_bf16 v[76:79], v[140:143], v[210:213], v[76:79]
	v_mfma_f32_16x16x32_bf16 v[128:131], v[136:139], v[186:189], v[128:131]
	v_mfma_f32_16x16x32_bf16 v[124:127], v[144:147], v[186:189], v[124:127]
	v_mfma_f32_16x16x32_bf16 v[112:115], v[136:139], v[198:201], v[112:115]
	v_mfma_f32_16x16x32_bf16 v[108:111], v[144:147], v[198:201], v[108:111]
	v_mfma_f32_16x16x32_bf16 v[96:99], v[136:139], v[206:209], v[96:99]
	v_mfma_f32_16x16x32_bf16 v[92:95], v[144:147], v[206:209], v[92:95]
	v_mfma_f32_16x16x32_bf16 v[80:83], v[136:139], v[234:237], v[80:83]
	v_mfma_f32_16x16x32_bf16 v[76:79], v[144:147], v[234:237], v[76:79]
	s_setprio 0
	s_setprio 1
	v_mfma_f32_16x16x32_bf16 v[120:123], v[148:151], v[182:185], v[120:123]
	v_mfma_f32_16x16x32_bf16 v[116:119], v[156:159], v[182:185], v[116:119]
	v_mfma_f32_16x16x32_bf16 v[104:107], v[148:151], v[190:193], v[104:107]
	v_mfma_f32_16x16x32_bf16 v[100:103], v[156:159], v[190:193], v[100:103]
	v_mfma_f32_16x16x32_bf16 v[88:91], v[148:151], v[202:205], v[88:91]
	v_mfma_f32_16x16x32_bf16 v[84:87], v[156:159], v[202:205], v[84:87]
	v_mfma_f32_16x16x32_bf16 v[72:75], v[148:151], v[210:213], v[72:75]
	v_mfma_f32_16x16x32_bf16 v[68:71], v[156:159], v[210:213], v[68:71]
	v_mfma_f32_16x16x32_bf16 v[120:123], v[152:155], v[186:189], v[120:123]
	v_mfma_f32_16x16x32_bf16 v[116:119], v[178:181], v[186:189], v[116:119]
	v_mfma_f32_16x16x32_bf16 v[104:107], v[152:155], v[198:201], v[104:107]
	v_mfma_f32_16x16x32_bf16 v[100:103], v[178:181], v[198:201], v[100:103]
	v_mfma_f32_16x16x32_bf16 v[88:91], v[152:155], v[206:209], v[88:91]
	v_mfma_f32_16x16x32_bf16 v[84:87], v[178:181], v[206:209], v[84:87]
	v_mfma_f32_16x16x32_bf16 v[72:75], v[152:155], v[234:237], v[72:75]
	v_mfma_f32_16x16x32_bf16 v[68:71], v[178:181], v[234:237], v[68:71]
	s_setprio 0
	s_barrier
	s_add_i32 s6, s70, s56
	v_lshl_add_u64 v[238:239], v[238:239], 0, s[16:17]
	s_mov_b32 m0, s6
	ds_read_b128 v[182:185], v196 offset:49152
	ds_read_b128 v[186:189], v196 offset:50176
	ds_read_b128 v[190:193], v196 offset:51200
	ds_read_b128 v[198:201], v196 offset:52224
	ds_read_b128 v[202:205], v196 offset:53248
	ds_read_b128 v[206:209], v196 offset:54272
	ds_read_b128 v[210:213], v196 offset:55296
	ds_read_b128 v[234:237], v196 offset:56320
	global_load_lds_dwordx4 v[238:239], off
	s_add_i32 m0, s6, 0x2000
	s_add_u32 s6, s18, 0xb0080
	v_lshl_add_u64 v[238:239], v[240:241], 0, s[16:17]
	s_addc_u32 s7, s19, 0
	s_add_i32 s18, s71, s56
	global_load_lds_dwordx4 v[238:239], off
	v_lshl_add_u64 v[238:239], s[6:7], 0, v[2:3]
	s_mov_b32 m0, s18
	s_nop 0
	global_load_lds_dwordx4 v[238:239], off
	v_lshl_add_u64 v[238:239], s[6:7], 0, v[160:161]
	s_add_i32 m0, s18, 0x2000
	s_nop 0
	global_load_lds_dwordx4 v[238:239], off
	v_lshl_add_u64 v[238:239], v[242:243], 0, s[16:17]
	s_mov_b32 m0, s34
	s_nop 0
	global_load_lds_dwordx4 v[238:239], off
	v_lshl_add_u64 v[238:239], v[244:245], 0, s[16:17]
	s_mov_b32 m0, s65
	s_nop 0
	global_load_lds_dwordx4 v[238:239], off
	s_waitcnt vmcnt(8)
	s_waitcnt lgkmcnt(0)
	s_barrier
	s_setprio 1
	s_waitcnt lgkmcnt(0)
	v_mfma_f32_16x16x32_bf16 v[64:67], v[132:135], v[182:185], v[64:67]
	v_mfma_f32_16x16x32_bf16 v[60:63], v[140:143], v[182:185], v[60:63]
	v_mfma_f32_16x16x32_bf16 v[48:51], v[132:135], v[190:193], v[48:51]
	v_mfma_f32_16x16x32_bf16 v[44:47], v[140:143], v[190:193], v[44:47]
	v_mfma_f32_16x16x32_bf16 v[32:35], v[132:135], v[202:205], v[32:35]
	v_mfma_f32_16x16x32_bf16 v[28:31], v[140:143], v[202:205], v[28:31]
	v_mfma_f32_16x16x32_bf16 v[16:19], v[132:135], v[210:213], v[16:19]
	v_mfma_f32_16x16x32_bf16 v[12:15], v[140:143], v[210:213], v[12:15]
	v_mfma_f32_16x16x32_bf16 v[64:67], v[136:139], v[186:189], v[64:67]
	v_mfma_f32_16x16x32_bf16 v[60:63], v[144:147], v[186:189], v[60:63]
	v_mfma_f32_16x16x32_bf16 v[48:51], v[136:139], v[198:201], v[48:51]
	v_mfma_f32_16x16x32_bf16 v[44:47], v[144:147], v[198:201], v[44:47]
	v_mfma_f32_16x16x32_bf16 v[32:35], v[136:139], v[206:209], v[32:35]
	v_mfma_f32_16x16x32_bf16 v[28:31], v[144:147], v[206:209], v[28:31]
	v_mfma_f32_16x16x32_bf16 v[16:19], v[136:139], v[234:237], v[16:19]
	v_mfma_f32_16x16x32_bf16 v[12:15], v[144:147], v[234:237], v[12:15]
	s_setprio 0
	s_setprio 1
	v_mfma_f32_16x16x32_bf16 v[56:59], v[148:151], v[182:185], v[56:59]
	v_mfma_f32_16x16x32_bf16 v[52:55], v[156:159], v[182:185], v[52:55]
	v_mfma_f32_16x16x32_bf16 v[40:43], v[148:151], v[190:193], v[40:43]
	v_mfma_f32_16x16x32_bf16 v[36:39], v[156:159], v[190:193], v[36:39]
	v_mfma_f32_16x16x32_bf16 v[24:27], v[148:151], v[202:205], v[24:27]
	v_mfma_f32_16x16x32_bf16 v[20:23], v[156:159], v[202:205], v[20:23]
	v_mfma_f32_16x16x32_bf16 v[8:11], v[148:151], v[210:213], v[8:11]
	v_mfma_f32_16x16x32_bf16 v[4:7], v[156:159], v[210:213], v[4:7]
	v_mfma_f32_16x16x32_bf16 v[56:59], v[152:155], v[186:189], v[56:59]
	v_mfma_f32_16x16x32_bf16 v[52:55], v[178:181], v[186:189], v[52:55]
	v_mfma_f32_16x16x32_bf16 v[40:43], v[152:155], v[198:201], v[40:43]
	v_mfma_f32_16x16x32_bf16 v[36:39], v[178:181], v[198:201], v[36:39]
	v_mfma_f32_16x16x32_bf16 v[24:27], v[152:155], v[206:209], v[24:27]
	v_mfma_f32_16x16x32_bf16 v[20:23], v[178:181], v[206:209], v[20:23]
	v_mfma_f32_16x16x32_bf16 v[8:11], v[152:155], v[234:237], v[8:11]
	v_mfma_f32_16x16x32_bf16 v[4:7], v[178:181], v[234:237], v[4:7]
	s_setprio 0
	s_barrier
	s_add_i32 s69, s69, 2
	s_add_u32 s14, s14, 0x100
	s_addc_u32 s15, s15, 0
	s_cmp_gt_u32 s69, 41
	s_mov_b64 s[6:7], s[4:5]
